# QKV epilogue: 4 norm-scale loads issued together (one wait); rmsnorm+mod copy at LBB0_1483: all 16 row loads hoisted to the top with counted vmcnt
# baseline (speedup 1.0000x reference)
; #define PG8_STAGE(bufoff, gbase) do { _Pragma("unroll") for (int _i = 0; _i < 2; ++_i) \
;         __builtin_amdgcn_global_load_lds((const unsigned*)((const char*)(gbase) + voff[_i]), (LAS unsigned*)(lds + (bufoff) + ldsw + _i * 8192), 16, 0, 0); } while (0)
; #define PG8_LDA(dst, b, h) do { _Pragma("unroll") for (int m = 0; m < 4; ++m) _Pragma("unroll") for (int k = 0; k < 2; ++k) dst[m][k] = *(const LAS bf16x8*)(lds + PG8_SA(b, h) + aoff + m * 2048 + k * 1024); } while (0)
; #define PG8_LDB(dst, b, h) do { _Pragma("unroll") for (int n = 0; n < 2; ++n) _Pragma("unroll") for (int k = 0; k < 2; ++k) dst[n][k] = *(const LAS bf16x8*)(lds + PG8_SB(b, h) + boff + n * 2048 + k * 1024); } while (0)
; #define PG8_WAIT_V(n) asm volatile("s_waitcnt vmcnt(" #n ")" ::: "memory")
; #define PG8_WAIT_L(n) asm volatile("s_waitcnt lgkmcnt(" #n ")" ::: "memory")
; #define PG8_BAR __builtin_amdgcn_s_barrier()
; #define PG8_SCHED __builtin_amdgcn_sched_barrier(0)
;     ...
;             PG8_LDB(B0, 0, 0); PG8_SCHED; PG8_LDA(At, 0, 0); PG8_STAGE(PG8_SA(1, 1), a1 + hstep);
;             PG8_WAIT_L(8); PG8_BAR; PG8_WAIT_L(0); PG8_MMA(0, 0, At, B0); PG8_BAR; PG8_SCHED;
;             PG8_LDB(B1, 0, 1); PG8_STAGE(PG8_SB(0, 0), b2);
;             PG8_BAR; PG8_WAIT_L(0); PG8_MMA(0, 1, At, B1); PG8_BAR;
;             PG8_LDA(At, 0, 1); PG8_STAGE(PG8_SA(0, 0), a2);
;             PG8_BAR; PG8_WAIT_L(0); PG8_MMA(1, 0, At, B0); PG8_BAR; PG8_SCHED;
;             PG8_STAGE(PG8_SB(0, 1), b2 + hstep);
;             PG8_WAIT_V(6); PG8_BAR; PG8_MMA(1, 1, At, B1); PG8_BAR;
;             PG8_LDB(B0, 1, 0); PG8_SCHED; PG8_LDA(At, 1, 0); PG8_STAGE(PG8_SA(0, 1), a2 + hstep);
;             PG8_WAIT_L(8); PG8_BAR; PG8_WAIT_L(0); PG8_MMA(0, 0, At, B0); PG8_BAR; PG8_SCHED;
.LBB0_161:
	s_add_u32 s0, s10, 0xfffc0080
	s_addc_u32 s1, s11, -1
	s_add_i32 s29, 0, 0x10000
	v_add_u32_e32 v162, s29, v1
	ds_read_b128 v[158:161], v162
	ds_read_b128 v[168:171], v162 offset:1024
	ds_read_b128 v[172:175], v162 offset:2048
	ds_read_b128 v[194:197], v162 offset:3072
	s_cmp_eq_u32 s28, 12
	s_cselect_b32 s15, s4, s1
	s_cselect_b32 s14, s7, s0
	s_cselect_b32 s13, s18, s23
	s_cselect_b32 s12, s19, s22
	v_lshl_add_u64 v[162:163], s[10:11], 0, v[154:155]
	s_add_i32 m0, s17, 0xc000
	ds_read_b128 v[198:201], v166
	ds_read_b128 v[202:205], v166 offset:1024
	ds_read_b128 v[206:209], v166 offset:2048
	ds_read_b128 v[210:213], v166 offset:3072
	ds_read_b128 v[214:217], v166 offset:4096
	ds_read_b128 v[218:221], v166 offset:5120
	ds_read_b128 v[222:225], v166 offset:6144
	ds_read_b128 v[226:229], v166 offset:7168
	global_load_lds_dwordx4 v[162:163], off
	s_add_i32 m0, s17, 0xe000
	v_lshl_add_u64 v[162:163], s[10:11], 0, v[156:157]
	global_load_lds_dwordx4 v[162:163], off
	s_waitcnt lgkmcnt(8)
	s_barrier
	s_waitcnt lgkmcnt(0)
	s_setprio 1
	v_mfma_f32_16x16x32_bf16 v[126:129], v[198:201], v[158:161], v[126:129]
	v_mfma_f32_16x16x32_bf16 v[110:113], v[198:201], v[172:175], v[110:113]
	v_mfma_f32_16x16x32_bf16 v[122:125], v[206:209], v[158:161], v[122:125]
	v_mfma_f32_16x16x32_bf16 v[106:109], v[206:209], v[172:175], v[106:109]
	v_mfma_f32_16x16x32_bf16 v[118:121], v[214:217], v[158:161], v[118:121]
	v_mfma_f32_16x16x32_bf16 v[102:105], v[214:217], v[172:175], v[102:105]
	v_mfma_f32_16x16x32_bf16 v[114:117], v[222:225], v[158:161], v[114:117]
	v_mfma_f32_16x16x32_bf16 v[94:97], v[222:225], v[172:175], v[94:97]
	v_mfma_f32_16x16x32_bf16 v[126:129], v[202:205], v[168:171], v[126:129]
	v_mfma_f32_16x16x32_bf16 v[110:113], v[202:205], v[194:197], v[110:113]
	v_mfma_f32_16x16x32_bf16 v[122:125], v[210:213], v[168:171], v[122:125]
	v_mfma_f32_16x16x32_bf16 v[106:109], v[210:213], v[194:197], v[106:109]
	v_mfma_f32_16x16x32_bf16 v[118:121], v[218:221], v[168:171], v[118:121]
	v_mfma_f32_16x16x32_bf16 v[102:105], v[218:221], v[194:197], v[102:105]
	v_mfma_f32_16x16x32_bf16 v[114:117], v[226:229], v[168:171], v[114:117]
	v_mfma_f32_16x16x32_bf16 v[94:97], v[226:229], v[194:197], v[94:97]
	s_setprio 0
	s_barrier
	s_add_i32 s0, 0, 0x14000
	v_add_u32_e32 v162, s0, v1
	s_add_i32 s1, s29, s16
	ds_read_b128 v[230:233], v162
	ds_read_b128 v[234:237], v162 offset:1024
	ds_read_b128 v[238:241], v162 offset:2048
	ds_read_b128 v[242:245], v162 offset:3072
	v_lshl_add_u64 v[162:163], s[12:13], 0, v[132:133]
	s_mov_b32 m0, s1
	v_lshl_add_u64 v[246:247], s[12:13], 0, v[130:131]
	global_load_lds_dwordx4 v[162:163], off
	s_add_i32 m0, s1, 0x2000
	s_nop 0
	global_load_lds_dwordx4 v[246:247], off
	s_barrier
	s_waitcnt lgkmcnt(0)
	s_setprio 1
	v_mfma_f32_16x16x32_bf16 v[82:85], v[198:201], v[230:233], v[82:85]
	v_mfma_f32_16x16x32_bf16 v[50:53], v[198:201], v[238:241], v[50:53]
	v_mfma_f32_16x16x32_bf16 v[74:77], v[206:209], v[230:233], v[74:77]
	v_mfma_f32_16x16x32_bf16 v[42:45], v[206:209], v[238:241], v[42:45]
	v_mfma_f32_16x16x32_bf16 v[66:69], v[214:217], v[230:233], v[66:69]
	v_mfma_f32_16x16x32_bf16 v[38:41], v[214:217], v[238:241], v[38:41]
	v_mfma_f32_16x16x32_bf16 v[58:61], v[222:225], v[230:233], v[58:61]
	v_mfma_f32_16x16x32_bf16 v[30:33], v[222:225], v[238:241], v[30:33]
	v_mfma_f32_16x16x32_bf16 v[82:85], v[202:205], v[234:237], v[82:85]
	v_mfma_f32_16x16x32_bf16 v[50:53], v[202:205], v[242:245], v[50:53]
	v_mfma_f32_16x16x32_bf16 v[74:77], v[210:213], v[234:237], v[74:77]
	v_mfma_f32_16x16x32_bf16 v[42:45], v[210:213], v[242:245], v[42:45]
	v_mfma_f32_16x16x32_bf16 v[66:69], v[218:221], v[234:237], v[66:69]
	v_mfma_f32_16x16x32_bf16 v[38:41], v[218:221], v[242:245], v[38:41]
	v_mfma_f32_16x16x32_bf16 v[58:61], v[226:229], v[234:237], v[58:61]
	v_mfma_f32_16x16x32_bf16 v[30:33], v[226:229], v[242:245], v[30:33]
	s_setprio 0
	s_mov_b32 m0, s17
	v_lshl_add_u64 v[248:249], s[14:15], 0, v[132:133]
	s_barrier
	ds_read_b128 v[198:201], v166 offset:16384
	ds_read_b128 v[202:205], v166 offset:17408
	ds_read_b128 v[206:209], v166 offset:18432
	ds_read_b128 v[210:213], v166 offset:19456
	ds_read_b128 v[214:217], v166 offset:20480
	ds_read_b128 v[218:221], v166 offset:21504
	ds_read_b128 v[222:225], v166 offset:22528
	ds_read_b128 v[226:229], v166 offset:23552
	global_load_lds_dwordx4 v[248:249], off
	s_mov_b32 m0, s20
	v_lshl_add_u64 v[192:193], s[14:15], 0, v[130:131]
	global_load_lds_dwordx4 v[192:193], off
	s_barrier
	s_waitcnt lgkmcnt(0)
	s_setprio 1
	v_mfma_f32_16x16x32_bf16 v[98:101], v[198:201], v[158:161], v[98:101]
	v_mfma_f32_16x16x32_bf16 v[70:73], v[198:201], v[172:175], v[70:73]
	v_mfma_f32_16x16x32_bf16 v[90:93], v[206:209], v[158:161], v[90:93]
	v_mfma_f32_16x16x32_bf16 v[62:65], v[206:209], v[172:175], v[62:65]
	v_mfma_f32_16x16x32_bf16 v[86:89], v[214:217], v[158:161], v[86:89]
	v_mfma_f32_16x16x32_bf16 v[54:57], v[214:217], v[172:175], v[54:57]
	v_mfma_f32_16x16x32_bf16 v[78:81], v[222:225], v[158:161], v[78:81]
	v_mfma_f32_16x16x32_bf16 v[46:49], v[222:225], v[172:175], v[46:49]
	v_mfma_f32_16x16x32_bf16 v[98:101], v[202:205], v[168:171], v[98:101]
	v_mfma_f32_16x16x32_bf16 v[70:73], v[202:205], v[194:197], v[70:73]
	v_mfma_f32_16x16x32_bf16 v[90:93], v[210:213], v[168:171], v[90:93]
	v_mfma_f32_16x16x32_bf16 v[62:65], v[210:213], v[194:197], v[62:65]
	v_mfma_f32_16x16x32_bf16 v[86:89], v[218:221], v[168:171], v[86:89]
	v_mfma_f32_16x16x32_bf16 v[54:57], v[218:221], v[194:197], v[54:57]
	v_mfma_f32_16x16x32_bf16 v[78:81], v[226:229], v[168:171], v[78:81]
	v_mfma_f32_16x16x32_bf16 v[46:49], v[226:229], v[194:197], v[46:49]
	s_setprio 0
	s_barrier
; #define PG8_STAGE(bufoff, gbase) do { _Pragma("unroll") for (int _i = 0; _i < 2; ++_i) \
;         __builtin_amdgcn_global_load_lds((const unsigned*)((const char*)(gbase) + voff[_i]), (LAS unsigned*)(lds + (bufoff) + ldsw + _i * 8192), 16, 0, 0); } while (0)
; #define PG8_LDA(dst, b, h) do { _Pragma("unroll") for (int m = 0; m < 4; ++m) _Pragma("unroll") for (int k = 0; k < 2; ++k) dst[m][k] = *(const LAS bf16x8*)(lds + PG8_SA(b, h) + aoff + m * 2048 + k * 1024); } while (0)
; #define PG8_LDB(dst, b, h) do { _Pragma("unroll") for (int n = 0; n < 2; ++n) _Pragma("unroll") for (int k = 0; k < 2; ++k) dst[n][k] = *(const LAS bf16x8*)(lds + PG8_SB(b, h) + boff + n * 2048 + k * 1024); } while (0)
; #define PG8_WAIT_V(n) asm volatile("s_waitcnt vmcnt(" #n ")" ::: "memory")
; #define PG8_WAIT_L(n) asm volatile("s_waitcnt lgkmcnt(" #n ")" ::: "memory")
; #define PG8_BAR __builtin_amdgcn_s_barrier()
; #define PG8_SCHED __builtin_amdgcn_sched_barrier(0)
;     ...
;             PG8_STAGE(PG8_SB(0, 1), b2 + hstep);
;             PG8_WAIT_V(6); PG8_BAR; PG8_MMA(1, 1, At, B1); PG8_BAR;
;             PG8_LDB(B0, 1, 0); PG8_SCHED; PG8_LDA(At, 1, 0); PG8_STAGE(PG8_SA(0, 1), a2 + hstep);
;             PG8_WAIT_L(8); PG8_BAR; PG8_WAIT_L(0); PG8_MMA(0, 0, At, B0); PG8_BAR; PG8_SCHED;
;             PG8_LDB(B1, 1, 1); PG8_STAGE(PG8_SB(1, 0), b3);
;             PG8_BAR; PG8_WAIT_L(0); PG8_MMA(0, 1, At, B1); PG8_BAR;
;             PG8_LDA(At, 1, 1); PG8_STAGE(PG8_SA(1, 0), a3);
;             PG8_BAR; PG8_WAIT_L(0); PG8_MMA(1, 0, At, B0); PG8_BAR; PG8_SCHED;
	s_add_u32 s30, s12, 0x40000
	s_addc_u32 s31, s13, 0
	s_add_i32 s0, s0, s16
	s_mov_b32 m0, s0
	v_lshl_add_u64 v[158:159], s[30:31], 0, v[132:133]
	global_load_lds_dwordx4 v[158:159], off
	s_add_i32 m0, s0, 0x2000
	v_lshl_add_u64 v[158:159], s[30:31], 0, v[130:131]
	global_load_lds_dwordx4 v[158:159], off
	s_waitcnt vmcnt(6)
	s_barrier
	s_setprio 1
	v_mfma_f32_16x16x32_bf16 v[34:37], v[198:201], v[230:233], v[34:37]
	v_mfma_f32_16x16x32_bf16 v[14:17], v[198:201], v[238:241], v[14:17]
	v_mfma_f32_16x16x32_bf16 v[26:29], v[206:209], v[230:233], v[26:29]
	v_mfma_f32_16x16x32_bf16 v[10:13], v[206:209], v[238:241], v[10:13]
	v_mfma_f32_16x16x32_bf16 v[22:25], v[214:217], v[230:233], v[22:25]
	v_mfma_f32_16x16x32_bf16 v[6:9], v[214:217], v[238:241], v[6:9]
	v_mfma_f32_16x16x32_bf16 v[18:21], v[222:225], v[230:233], v[18:21]
	v_mfma_f32_16x16x32_bf16 v[2:5], v[222:225], v[238:241], v[2:5]
	v_mfma_f32_16x16x32_bf16 v[34:37], v[202:205], v[234:237], v[34:37]
	v_mfma_f32_16x16x32_bf16 v[14:17], v[202:205], v[242:245], v[14:17]
	v_mfma_f32_16x16x32_bf16 v[26:29], v[210:213], v[234:237], v[26:29]
	v_mfma_f32_16x16x32_bf16 v[10:13], v[210:213], v[242:245], v[10:13]
	v_mfma_f32_16x16x32_bf16 v[22:25], v[218:221], v[234:237], v[22:25]
	v_mfma_f32_16x16x32_bf16 v[6:9], v[218:221], v[242:245], v[6:9]
	v_mfma_f32_16x16x32_bf16 v[18:21], v[226:229], v[234:237], v[18:21]
	v_mfma_f32_16x16x32_bf16 v[2:5], v[226:229], v[242:245], v[2:5]
	s_setprio 0
	s_add_i32 s0, 0, 0x18000
	v_add_u32_e32 v194, s0, v1
	s_barrier
	ds_read_b128 v[158:161], v194
	ds_read_b128 v[168:171], v194 offset:1024
	ds_read_b128 v[172:175], v194 offset:2048
	ds_read_b128 v[194:197], v194 offset:3072
	s_add_u32 s14, s14, 0x40000
	s_addc_u32 s15, s15, 0
	s_mov_b32 m0, s40
	v_lshl_add_u64 v[230:231], s[14:15], 0, v[132:133]
	ds_read_b128 v[198:201], v166 offset:32768
	ds_read_b128 v[202:205], v166 offset:33792
	ds_read_b128 v[206:209], v166 offset:34816
	ds_read_b128 v[210:213], v166 offset:35840
	ds_read_b128 v[214:217], v166 offset:36864
	ds_read_b128 v[218:221], v166 offset:37888
	ds_read_b128 v[222:225], v166 offset:38912
	ds_read_b128 v[226:229], v166 offset:39936
	global_load_lds_dwordx4 v[230:231], off
	s_mov_b32 m0, s41
	v_lshl_add_u64 v[230:231], s[14:15], 0, v[130:131]
	global_load_lds_dwordx4 v[230:231], off
	s_waitcnt lgkmcnt(8)
	s_barrier
	s_waitcnt lgkmcnt(0)
	s_setprio 1
	v_mfma_f32_16x16x32_bf16 v[126:129], v[198:201], v[158:161], v[126:129]
	v_mfma_f32_16x16x32_bf16 v[110:113], v[198:201], v[172:175], v[110:113]
	v_mfma_f32_16x16x32_bf16 v[122:125], v[206:209], v[158:161], v[122:125]
	v_mfma_f32_16x16x32_bf16 v[106:109], v[206:209], v[172:175], v[106:109]
	v_mfma_f32_16x16x32_bf16 v[118:121], v[214:217], v[158:161], v[118:121]
	v_mfma_f32_16x16x32_bf16 v[102:105], v[214:217], v[172:175], v[102:105]
	v_mfma_f32_16x16x32_bf16 v[114:117], v[222:225], v[158:161], v[114:117]
	v_mfma_f32_16x16x32_bf16 v[94:97], v[222:225], v[172:175], v[94:97]
	v_mfma_f32_16x16x32_bf16 v[126:129], v[202:205], v[168:171], v[126:129]
	v_mfma_f32_16x16x32_bf16 v[110:113], v[202:205], v[194:197], v[110:113]
	v_mfma_f32_16x16x32_bf16 v[122:125], v[210:213], v[168:171], v[122:125]
	v_mfma_f32_16x16x32_bf16 v[106:109], v[210:213], v[194:197], v[106:109]
	v_mfma_f32_16x16x32_bf16 v[118:121], v[218:221], v[168:171], v[118:121]
	v_mfma_f32_16x16x32_bf16 v[102:105], v[218:221], v[194:197], v[102:105]
	v_mfma_f32_16x16x32_bf16 v[114:117], v[226:229], v[168:171], v[114:117]
	v_mfma_f32_16x16x32_bf16 v[94:97], v[226:229], v[194:197], v[94:97]
	s_setprio 0
	s_barrier
	s_add_i32 s1, 0, 0x1c000
	s_add_i32 s0, s0, s16
	v_add_u32_e32 v242, s1, v1
	v_lshl_add_u64 v[162:163], v[162:163], 0, s[88:89]
	s_mov_b32 m0, s0
	ds_read_b128 v[230:233], v242
	ds_read_b128 v[234:237], v242 offset:1024
	ds_read_b128 v[238:241], v242 offset:2048
	ds_read_b128 v[242:245], v242 offset:3072
	global_load_lds_dwordx4 v[162:163], off
	s_add_i32 m0, s0, 0x2000
	v_lshl_add_u64 v[162:163], v[246:247], 0, s[88:89]
	global_load_lds_dwordx4 v[162:163], off
	s_barrier
	s_waitcnt lgkmcnt(0)
	s_setprio 1
	v_mfma_f32_16x16x32_bf16 v[82:85], v[198:201], v[230:233], v[82:85]
	v_mfma_f32_16x16x32_bf16 v[50:53], v[198:201], v[238:241], v[50:53]
	v_mfma_f32_16x16x32_bf16 v[74:77], v[206:209], v[230:233], v[74:77]
	v_mfma_f32_16x16x32_bf16 v[42:45], v[206:209], v[238:241], v[42:45]
	v_mfma_f32_16x16x32_bf16 v[66:69], v[214:217], v[230:233], v[66:69]
	v_mfma_f32_16x16x32_bf16 v[38:41], v[214:217], v[238:241], v[38:41]
	v_mfma_f32_16x16x32_bf16 v[58:61], v[222:225], v[230:233], v[58:61]
	v_mfma_f32_16x16x32_bf16 v[30:33], v[222:225], v[238:241], v[30:33]
	v_mfma_f32_16x16x32_bf16 v[82:85], v[202:205], v[234:237], v[82:85]
	v_mfma_f32_16x16x32_bf16 v[50:53], v[202:205], v[242:245], v[50:53]
	v_mfma_f32_16x16x32_bf16 v[74:77], v[210:213], v[234:237], v[74:77]
	v_mfma_f32_16x16x32_bf16 v[42:45], v[210:213], v[242:245], v[42:45]
	v_mfma_f32_16x16x32_bf16 v[66:69], v[218:221], v[234:237], v[66:69]
	v_mfma_f32_16x16x32_bf16 v[38:41], v[218:221], v[242:245], v[38:41]
	v_mfma_f32_16x16x32_bf16 v[58:61], v[226:229], v[234:237], v[58:61]
	v_mfma_f32_16x16x32_bf16 v[30:33], v[226:229], v[242:245], v[30:33]
	s_setprio 0
	s_mov_b32 m0, s58
	v_lshl_add_u64 v[162:163], v[248:249], 0, s[88:89]
	s_barrier
	ds_read_b128 v[198:201], v166 offset:49152
	ds_read_b128 v[202:205], v166 offset:50176
	ds_read_b128 v[206:209], v166 offset:51200
	ds_read_b128 v[210:213], v166 offset:52224
	ds_read_b128 v[214:217], v166 offset:53248
	ds_read_b128 v[218:221], v166 offset:54272
	ds_read_b128 v[222:225], v166 offset:55296
	ds_read_b128 v[226:229], v166 offset:56320
	global_load_lds_dwordx4 v[162:163], off
	s_mov_b32 m0, s59
	v_lshl_add_u64 v[162:163], v[192:193], 0, s[88:89]
	global_load_lds_dwordx4 v[162:163], off
	s_barrier
; #define PG8_STAGE(bufoff, gbase) do { _Pragma("unroll") for (int _i = 0; _i < 2; ++_i) \
;         __builtin_amdgcn_global_load_lds((const unsigned*)((const char*)(gbase) + voff[_i]), (LAS unsigned*)(lds + (bufoff) + ldsw + _i * 8192), 16, 0, 0); } while (0)
; #define PG8_WAIT_V(n) asm volatile("s_waitcnt vmcnt(" #n ")" ::: "memory")
; #define PG8_WAIT_L(n) asm volatile("s_waitcnt lgkmcnt(" #n ")" ::: "memory")
; #define PG8_BAR __builtin_amdgcn_s_barrier()
; #define PG8_SCHED __builtin_amdgcn_sched_barrier(0)
;     ...
;             PG8_BAR; PG8_WAIT_L(0); PG8_MMA(1, 0, At, B0); PG8_BAR; PG8_SCHED;
;             PG8_STAGE(PG8_SB(1, 1), b3 + hstep);
;             PG8_WAIT_V(6); PG8_BAR; PG8_MMA(1, 1, At, B1); PG8_BAR;
;     __device__ __forceinline__ void operator()(Acc& acc, int pm, int pn, int wr, int wc, int fr, int fq) const {
;         if (pn >= 8) { store_vT(acc, vT, (pn - 8) * 256, pm, wr, wc, fr, fq); return; }
;         const int head = pn * 4 + wc;
;         const bool isk = head >= 16;
;         const float* g = isk ? kg : qg;
;         const float sc = isk ? 1.0f : 0.125f;
;         float gv[2][2];
; #pragma unroll
;         for (int bj = 0; bj < 2; ++bj)
; #pragma unroll
;             for (int n = 0; n < 2; ++n) gv[bj][n] = g[bj * 32 + n * 16 + fr] * sc;
; #pragma unroll
;         for (int ai = 0; ai < 2; ++ai)
; #pragma unroll
;             for (int m = 0; m < 4; ++m)
; #pragma unroll
;                 for (int j = 0; j < 4; ++j) {
;                     float ss = acc[ai][0][m][0][j] * acc[ai][0][m][0][j] + acc[ai][0][m][1][j] * acc[ai][0][m][1][j] +
;                                acc[ai][1][m][0][j] * acc[ai][1][m][0][j] + acc[ai][1][m][1][j] * acc[ai][1][m][1][j];
;                     ss += __shfl_xor(ss, 1); ss += __shfl_xor(ss, 2); ss += __shfl_xor(ss, 4); ss += __shfl_xor(ss, 8);
;                     const float rs = rsqrtf(ss * (1.0f / 64.0f) + EPSV);
	s_waitcnt lgkmcnt(0)
	s_setprio 1
	v_mfma_f32_16x16x32_bf16 v[98:101], v[198:201], v[158:161], v[98:101]
	v_mfma_f32_16x16x32_bf16 v[70:73], v[198:201], v[172:175], v[70:73]
	v_mfma_f32_16x16x32_bf16 v[90:93], v[206:209], v[158:161], v[90:93]
	v_mfma_f32_16x16x32_bf16 v[62:65], v[206:209], v[172:175], v[62:65]
	v_mfma_f32_16x16x32_bf16 v[86:89], v[214:217], v[158:161], v[86:89]
	v_mfma_f32_16x16x32_bf16 v[54:57], v[214:217], v[172:175], v[54:57]
	v_mfma_f32_16x16x32_bf16 v[78:81], v[222:225], v[158:161], v[78:81]
	v_mfma_f32_16x16x32_bf16 v[46:49], v[222:225], v[172:175], v[46:49]
	v_mfma_f32_16x16x32_bf16 v[98:101], v[202:205], v[168:171], v[98:101]
	v_mfma_f32_16x16x32_bf16 v[70:73], v[202:205], v[194:197], v[70:73]
	v_mfma_f32_16x16x32_bf16 v[90:93], v[210:213], v[168:171], v[90:93]
	v_mfma_f32_16x16x32_bf16 v[62:65], v[210:213], v[194:197], v[62:65]
	v_mfma_f32_16x16x32_bf16 v[86:89], v[218:221], v[168:171], v[86:89]
	v_mfma_f32_16x16x32_bf16 v[54:57], v[218:221], v[194:197], v[54:57]
	v_mfma_f32_16x16x32_bf16 v[78:81], v[226:229], v[168:171], v[78:81]
	v_mfma_f32_16x16x32_bf16 v[46:49], v[226:229], v[194:197], v[46:49]
	s_setprio 0
	s_barrier
	s_add_u32 s12, s12, 0x40080
	s_addc_u32 s13, s13, 0
	s_add_i32 s0, s1, s16
	s_mov_b32 m0, s0
	v_lshl_add_u64 v[158:159], s[12:13], 0, v[132:133]
	global_load_lds_dwordx4 v[158:159], off
	s_add_i32 m0, s0, 0x2000
	v_lshl_add_u64 v[158:159], s[12:13], 0, v[130:131]
	global_load_lds_dwordx4 v[158:159], off
	s_waitcnt vmcnt(6)
	s_barrier
	s_setprio 1
	v_mfma_f32_16x16x32_bf16 v[34:37], v[198:201], v[230:233], v[34:37]
	v_mfma_f32_16x16x32_bf16 v[14:17], v[198:201], v[238:241], v[14:17]
	v_mfma_f32_16x16x32_bf16 v[26:29], v[206:209], v[230:233], v[26:29]
	v_mfma_f32_16x16x32_bf16 v[10:13], v[206:209], v[238:241], v[10:13]
	v_mfma_f32_16x16x32_bf16 v[22:25], v[214:217], v[230:233], v[22:25]
	v_mfma_f32_16x16x32_bf16 v[6:9], v[214:217], v[238:241], v[6:9]
	v_mfma_f32_16x16x32_bf16 v[18:21], v[222:225], v[230:233], v[18:21]
	v_mfma_f32_16x16x32_bf16 v[2:5], v[222:225], v[238:241], v[2:5]
	v_mfma_f32_16x16x32_bf16 v[34:37], v[202:205], v[234:237], v[34:37]
	v_mfma_f32_16x16x32_bf16 v[14:17], v[202:205], v[242:245], v[14:17]
	v_mfma_f32_16x16x32_bf16 v[26:29], v[210:213], v[234:237], v[26:29]
	v_mfma_f32_16x16x32_bf16 v[10:13], v[210:213], v[242:245], v[10:13]
	v_mfma_f32_16x16x32_bf16 v[22:25], v[218:221], v[234:237], v[22:25]
	v_mfma_f32_16x16x32_bf16 v[6:9], v[218:221], v[242:245], v[6:9]
	v_mfma_f32_16x16x32_bf16 v[18:21], v[226:229], v[234:237], v[18:21]
	v_mfma_f32_16x16x32_bf16 v[2:5], v[226:229], v[242:245], v[2:5]
	s_setprio 0
	s_add_i32 s28, s28, 2
	s_add_u32 s10, s10, 0x100
	s_addc_u32 s11, s11, 0
	s_add_u32 s22, s22, 0x100
	s_addc_u32 s23, s23, 0
	s_cmp_gt_u32 s28, 13
	s_barrier
	s_cbranch_scc0 .LBB0_161
	s_cmp_lt_i32 s95, 8
	s_mov_b64 s[10:11], -1
	s_cbranch_scc0 .LBB0_164
	s_lshl_b32 s0, s95, 2
	s_or_b32 s0, s0, s90
	s_cmp_gt_i32 s0, 15
	s_cselect_b64 s[10:11], -1, 0
	v_readlane_b32 s60, v254, 42
	v_cndmask_b32_e64 v158, v189, 1.0, s[10:11]
	s_and_b64 s[10:11], s[10:11], exec
	v_readlane_b32 s72, v254, 54
	v_readlane_b32 s73, v254, 55
	v_readlane_b32 s74, v254, 56
	v_readlane_b32 s75, v254, 57
	s_cselect_b32 s11, s75, s73
	s_cselect_b32 s10, s74, s72
	global_load_dword v159, v167, s[10:11]
	global_load_dword v169, v167, s[10:11] offset:64
	global_load_dword v170, v167, s[10:11] offset:128
	global_load_dword v171, v167, s[10:11] offset:192
	v_mov_b32_e32 v162, v126
	v_mov_b32_e32 v163, v110
	v_mov_b32_e32 v198, v127
	v_mov_b32_e32 v199, v111
	v_pk_mul_f32 v[162:163], v[162:163], v[162:163]
	v_mov_b32_e32 v194, v82
	v_mov_b32_e32 v195, v50
	v_pk_mul_f32 v[198:199], v[198:199], v[198:199]
	v_mov_b32_e32 v200, v83
	v_mov_b32_e32 v201, v51
	v_pk_mul_f32 v[194:195], v[194:195], v[194:195]
	v_pk_mul_f32 v[200:201], v[200:201], v[200:201]
	v_mov_b32_e32 v202, v198
	v_mov_b32_e32 v203, v162
	v_mov_b32_e32 v162, v199
	v_cmp_lt_i32_e32 vcc, v188, v182
	v_pk_add_f32 v[162:163], v[202:203], v[162:163]
	v_mov_b32_e32 v198, v200
	v_mov_b32_e32 v199, v194
	v_pk_add_f32 v[162:163], v[162:163], v[198:199]
	v_mov_b32_e32 v194, v201
	v_pk_add_f32 v[162:163], v[162:163], v[194:195]
	s_mov_b32 s4, 0x358637bd
	v_lshl_add_u32 v160, s5, 8, v164
	v_ashrrev_i32_e32 v161, 31, v160
	v_lshlrev_b64 v[196:197], 12, v[160:161]
	v_mov_b32_e32 v200, v129
	v_mov_b32_e32 v201, v113
	v_pk_mul_f32 v[200:201], v[200:201], v[200:201]
	v_mov_b32_e32 v202, v85
	v_mov_b32_e32 v203, v53
	v_pk_mul_f32 v[202:203], v[202:203], v[202:203]
	v_mov_b32_e32 v204, v200
	v_mov_b32_e32 v200, v202
	v_or_b32_e32 v198, 2, v160
	v_ashrrev_i32_e32 v199, 31, v198
	v_lshlrev_b64 v[198:199], 12, v[198:199]
	v_mov_b32_e32 v202, v75
	v_readlane_b32 s74, v255, 22
	v_readlane_b32 s61, v254, 43
	v_readlane_b32 s62, v254, 44
	v_readlane_b32 s63, v254, 45
	v_readlane_b32 s64, v254, 46
	v_readlane_b32 s65, v254, 47
	v_readlane_b32 s66, v254, 48
	v_readlane_b32 s67, v254, 49
	v_readlane_b32 s68, v254, 50
	v_readlane_b32 s69, v254, 51
	v_readlane_b32 s70, v254, 52
	v_readlane_b32 s71, v254, 53
	v_readlane_b32 s75, v255, 23
	s_waitcnt vmcnt(0)
	v_mul_f32_e32 v168, v158, v159
	v_mul_f32_e32 v169, v158, v169
	v_mul_f32_e32 v170, v158, v170
	s_lshl_b32 s10, s0, 6
	s_ashr_i32 s11, s10, 31
	v_mul_f32_e32 v171, v158, v171
	v_cndmask_b32_e32 v158, v180, v188, vcc
	v_lshlrev_b32_e32 v175, 2, v158
	ds_bpermute_b32 v195, v175, v163
	ds_bpermute_b32 v194, v175, v162
	v_cmp_lt_i32_e32 vcc, v187, v182
	s_waitcnt lgkmcnt(0)
	v_pk_add_f32 v[162:163], v[162:163], v[194:195]
	v_cndmask_b32_e32 v158, v180, v187, vcc
	v_lshlrev_b32_e32 v174, 2, v158
	ds_bpermute_b32 v195, v174, v163
	ds_bpermute_b32 v194, v174, v162
	v_cmp_lt_i32_e32 vcc, v186, v182
	s_waitcnt lgkmcnt(0)
; __device__ __forceinline__ unsigned f2bf(float f) { const __bf16 b = (__bf16)f; return (unsigned)__builtin_bit_cast(unsigned short, b); }
;     __device__ __forceinline__ void operator()(Acc& acc, int pm, int pn, int wr, int wc, int fr, int fq) const {
;     ...
;                     float ss = acc[ai][0][m][0][j] * acc[ai][0][m][0][j] + acc[ai][0][m][1][j] * acc[ai][0][m][1][j] +
;                                acc[ai][1][m][0][j] * acc[ai][1][m][0][j] + acc[ai][1][m][1][j] * acc[ai][1][m][1][j];
;                     ss += __shfl_xor(ss, 1); ss += __shfl_xor(ss, 2); ss += __shfl_xor(ss, 4); ss += __shfl_xor(ss, 8);
;                     const float rs = rsqrtf(ss * (1.0f / 64.0f) + EPSV);
;                     bf16_t* rp = qk + (size_t)(pm * 256 + ai * 128 + wr * 64 + m * 16 + fq * 4 + j) * 2048 + head * 64 + fr;
; #pragma unroll
;                     for (int bj = 0; bj < 2; ++bj)
; #pragma unroll
;                         for (int n = 0; n < 2; ++n) rp[bj * 32 + n * 16] = (bf16_t)f2bf(acc[ai][bj][m][n][j] * rs * gv[bj][n]);
;                 }
	v_pk_add_f32 v[162:163], v[162:163], v[194:195]
	v_cndmask_b32_e32 v158, v180, v186, vcc
	v_lshlrev_b32_e32 v173, 2, v158
	ds_bpermute_b32 v195, v173, v163
	ds_bpermute_b32 v194, v173, v162
	v_cmp_lt_i32_e32 vcc, v185, v182
	s_waitcnt lgkmcnt(0)
	v_pk_add_f32 v[162:163], v[162:163], v[194:195]
	v_cndmask_b32_e32 v158, v180, v185, vcc
	v_lshlrev_b32_e32 v172, 2, v158
	ds_bpermute_b32 v195, v172, v163
	ds_bpermute_b32 v194, v172, v162
	v_lshl_add_u64 v[158:159], s[10:11], 1, v[150:151]
	v_lshl_add_u64 v[196:197], v[158:159], 0, v[196:197]
	v_lshl_add_u64 v[198:199], v[158:159], 0, v[198:199]
	s_mov_b64 s[10:11], 0
	s_waitcnt lgkmcnt(0)
	v_pk_add_f32 v[194:195], v[162:163], v[194:195]
	v_mov_b64_e32 v[162:163], s[4:5]
	v_pk_fma_f32 v[194:195], v[194:195], s[8:9], v[162:163] op_sel_hi:[1,0,0]
	s_nop 0
	v_mul_f32_e32 v161, 0x4b800000, v195
	v_cmp_gt_f32_e64 s[46:47], s93, v195
	v_cmp_gt_f32_e32 vcc, s93, v194
	s_nop 0
	v_cndmask_b32_e64 v161, v195, v161, s[46:47]
	v_rsq_f32_e32 v161, v161
	s_nop 0
	v_mul_f32_e32 v192, 0x45800000, v161
	v_cndmask_b32_e64 v161, v161, v192, s[46:47]
	v_mul_f32_e32 v192, v126, v161
	v_mul_f32_e32 v192, v168, v192
	v_cvt_pk_bf16_f32 v192, v192, s0
	global_store_short v[196:197], v192, off
	v_mul_f32_e32 v192, v110, v161
	v_mul_f32_e32 v192, v169, v192
	v_cvt_pk_bf16_f32 v192, v192, s0
	global_store_short v[196:197], v192, off offset:32
	v_mul_f32_e32 v192, v82, v161
	v_mul_f32_e32 v161, v50, v161
	v_mul_f32_e32 v161, v171, v161
	v_cvt_pk_bf16_f32 v161, v161, s0
	global_store_short v[196:197], v161, off offset:96
	v_mul_f32_e32 v161, 0x4b800000, v194
	v_cndmask_b32_e32 v161, v194, v161, vcc
	v_rsq_f32_e32 v161, v161
	v_mul_f32_e32 v192, v170, v192
	v_cvt_pk_bf16_f32 v192, v192, s0
	global_store_short v[196:197], v192, off offset:64
	v_mul_f32_e32 v192, 0x45800000, v161
	v_cndmask_b32_e32 v161, v161, v192, vcc
	v_or_b32_e32 v194, 1, v160
	v_ashrrev_i32_e32 v195, 31, v194
	v_mul_f32_e32 v192, v127, v161
	v_lshlrev_b64 v[194:195], 12, v[194:195]
	v_mul_f32_e32 v192, v168, v192
	v_lshl_add_u64 v[194:195], v[158:159], 0, v[194:195]
	v_cvt_pk_bf16_f32 v192, v192, s0
	global_store_short v[194:195], v192, off
	v_mul_f32_e32 v192, v111, v161
	v_mul_f32_e32 v192, v169, v192
	v_cvt_pk_bf16_f32 v192, v192, s0
	global_store_short v[194:195], v192, off offset:32
	v_mul_f32_e32 v192, v83, v161
	v_mul_f32_e32 v161, v51, v161
	v_mul_f32_e32 v192, v170, v192
	v_mul_f32_e32 v161, v171, v161
	v_cvt_pk_bf16_f32 v192, v192, s0
	v_cvt_pk_bf16_f32 v161, v161, s0
	global_store_short v[194:195], v192, off offset:64
	global_store_short v[194:195], v161, off offset:96
	v_mov_b32_e32 v194, v128
	v_mov_b32_e32 v195, v112
	v_pk_mul_f32 v[194:195], v[194:195], v[194:195]
	v_mov_b32_e32 v196, v84
	v_mov_b32_e32 v197, v52
	v_pk_mul_f32 v[196:197], v[196:197], v[196:197]
	v_mov_b32_e32 v205, v194
	v_mov_b32_e32 v194, v201
	v_pk_add_f32 v[194:195], v[204:205], v[194:195]
	v_mov_b32_e32 v201, v196
	v_pk_add_f32 v[194:195], v[194:195], v[200:201]
	v_mov_b32_e32 v196, v203
	v_pk_add_f32 v[194:195], v[194:195], v[196:197]
	ds_bpermute_b32 v197, v175, v195
	ds_bpermute_b32 v196, v175, v194
	v_mov_b32_e32 v200, v123
	v_mov_b32_e32 v201, v107
	v_pk_mul_f32 v[200:201], v[200:201], v[200:201]
	v_mov_b32_e32 v203, v43
	s_waitcnt lgkmcnt(0)
	v_pk_add_f32 v[194:195], v[194:195], v[196:197]
	ds_bpermute_b32 v197, v174, v195
	ds_bpermute_b32 v196, v174, v194
	v_pk_mul_f32 v[202:203], v[202:203], v[202:203]
	v_mov_b32_e32 v204, v200
	v_mov_b32_e32 v200, v202
	v_mov_b32_e32 v202, v77
	s_waitcnt lgkmcnt(0)
	v_pk_add_f32 v[194:195], v[194:195], v[196:197]
	ds_bpermute_b32 v197, v173, v195
	ds_bpermute_b32 v196, v173, v194
	s_waitcnt lgkmcnt(0)
	v_pk_add_f32 v[194:195], v[194:195], v[196:197]
	ds_bpermute_b32 v197, v172, v195
	ds_bpermute_b32 v196, v172, v194
	s_waitcnt lgkmcnt(0)
	v_pk_add_f32 v[194:195], v[194:195], v[196:197]
	s_nop 0
	v_pk_fma_f32 v[194:195], v[194:195], s[8:9], v[162:163] op_sel_hi:[1,0,0]
	v_mov_b32_e32 v196, v122
	v_mul_f32_e32 v161, 0x4b800000, v195
	v_cmp_gt_f32_e64 s[46:47], s93, v195
	v_mov_b32_e32 v197, v106
	v_pk_mul_f32 v[196:197], v[196:197], v[196:197]
	v_cndmask_b32_e64 v161, v195, v161, s[46:47]
	v_rsq_f32_e32 v161, v161
	v_mov_b32_e32 v205, v196
	v_mov_b32_e32 v196, v201
	v_pk_add_f32 v[196:197], v[204:205], v[196:197]
	v_mul_f32_e32 v192, 0x45800000, v161
	v_cndmask_b32_e64 v161, v161, v192, s[46:47]
	v_mul_f32_e32 v192, v128, v161
	v_mul_f32_e32 v192, v168, v192
	v_cvt_pk_bf16_f32 v192, v192, s0
	global_store_short v[198:199], v192, off
	v_mul_f32_e32 v192, v112, v161
	v_mul_f32_e32 v192, v169, v192
	v_cvt_pk_bf16_f32 v192, v192, s0
	global_store_short v[198:199], v192, off offset:32
	v_mul_f32_e32 v192, v84, v161
	v_mul_f32_e32 v161, v52, v161
	v_mul_f32_e32 v192, v170, v192
	v_mul_f32_e32 v161, v171, v161
	v_cvt_pk_bf16_f32 v192, v192, s0
	v_cvt_pk_bf16_f32 v161, v161, s0
	global_store_short v[198:199], v192, off offset:64
	global_store_short v[198:199], v161, off offset:96
	v_mov_b32_e32 v198, v74
	v_mov_b32_e32 v199, v42
	v_pk_mul_f32 v[198:199], v[198:199], v[198:199]
	v_cmp_gt_f32_e32 vcc, s93, v194
	v_mov_b32_e32 v201, v198
	v_pk_add_f32 v[196:197], v[196:197], v[200:201]
	v_mov_b32_e32 v198, v203
	v_pk_add_f32 v[196:197], v[196:197], v[198:199]
	ds_bpermute_b32 v199, v175, v197
	ds_bpermute_b32 v198, v175, v196
	v_mul_f32_e32 v161, 0x4b800000, v194
	v_cndmask_b32_e32 v161, v194, v161, vcc
	v_rsq_f32_e32 v161, v161
	v_or_b32_e32 v194, 3, v160
	s_waitcnt lgkmcnt(0)
	v_pk_add_f32 v[196:197], v[196:197], v[198:199]
	ds_bpermute_b32 v199, v174, v197
	ds_bpermute_b32 v198, v174, v196
	v_mul_f32_e32 v192, 0x45800000, v161
	v_cndmask_b32_e32 v161, v161, v192, vcc
	v_ashrrev_i32_e32 v195, 31, v194
	v_mul_f32_e32 v192, v129, v161
	s_waitcnt lgkmcnt(0)
; __device__ __forceinline__ unsigned f2bf(float f) { const __bf16 b = (__bf16)f; return (unsigned)__builtin_bit_cast(unsigned short, b); }
;     __device__ __forceinline__ void operator()(Acc& acc, int pm, int pn, int wr, int wc, int fr, int fq) const {
;     ...
;                     float ss = acc[ai][0][m][0][j] * acc[ai][0][m][0][j] + acc[ai][0][m][1][j] * acc[ai][0][m][1][j] +
;                                acc[ai][1][m][0][j] * acc[ai][1][m][0][j] + acc[ai][1][m][1][j] * acc[ai][1][m][1][j];
;                     ss += __shfl_xor(ss, 1); ss += __shfl_xor(ss, 2); ss += __shfl_xor(ss, 4); ss += __shfl_xor(ss, 8);
;                     const float rs = rsqrtf(ss * (1.0f / 64.0f) + EPSV);
;                     bf16_t* rp = qk + (size_t)(pm * 256 + ai * 128 + wr * 64 + m * 16 + fq * 4 + j) * 2048 + head * 64 + fr;
; #pragma unroll
;                     for (int bj = 0; bj < 2; ++bj)
; #pragma unroll
;                         for (int n = 0; n < 2; ++n) rp[bj * 32 + n * 16] = (bf16_t)f2bf(acc[ai][bj][m][n][j] * rs * gv[bj][n]);
;                 }
	v_pk_add_f32 v[196:197], v[196:197], v[198:199]
	ds_bpermute_b32 v199, v173, v197
	ds_bpermute_b32 v198, v173, v196
	v_lshlrev_b64 v[194:195], 12, v[194:195]
	v_mul_f32_e32 v192, v168, v192
	v_lshl_add_u64 v[194:195], v[158:159], 0, v[194:195]
	v_cvt_pk_bf16_f32 v192, v192, s0
	s_waitcnt lgkmcnt(0)
	v_pk_add_f32 v[196:197], v[196:197], v[198:199]
	ds_bpermute_b32 v199, v172, v197
	ds_bpermute_b32 v198, v172, v196
	global_store_short v[194:195], v192, off
	v_mul_f32_e32 v192, v113, v161
	v_mul_f32_e32 v192, v169, v192
	v_cvt_pk_bf16_f32 v192, v192, s0
	global_store_short v[194:195], v192, off offset:32
	v_mul_f32_e32 v192, v85, v161
	v_mul_f32_e32 v161, v53, v161
	v_mul_f32_e32 v161, v171, v161
	s_waitcnt lgkmcnt(0)
	v_pk_add_f32 v[196:197], v[196:197], v[198:199]
	v_cvt_pk_bf16_f32 v161, v161, s0
	v_pk_fma_f32 v[196:197], v[196:197], s[8:9], v[162:163] op_sel_hi:[1,0,0]
	global_store_short v[194:195], v161, off offset:96
	v_mul_f32_e32 v161, 0x4b800000, v197
	v_cmp_gt_f32_e64 s[46:47], s93, v197
	v_mul_f32_e32 v192, v170, v192
	v_cvt_pk_bf16_f32 v192, v192, s0
	v_cndmask_b32_e64 v161, v197, v161, s[46:47]
	v_rsq_f32_e32 v161, v161
	global_store_short v[194:195], v192, off offset:64
	v_or_b32_e32 v194, 16, v160
	v_ashrrev_i32_e32 v195, 31, v194
	v_mul_f32_e32 v192, 0x45800000, v161
	v_cndmask_b32_e64 v161, v161, v192, s[46:47]
	v_mul_f32_e32 v192, v122, v161
	v_lshlrev_b64 v[194:195], 12, v[194:195]
	v_mul_f32_e32 v192, v168, v192
	v_lshl_add_u64 v[194:195], v[158:159], 0, v[194:195]
	v_cvt_pk_bf16_f32 v192, v192, s0
	global_store_short v[194:195], v192, off
	v_mul_f32_e32 v192, v106, v161
	v_mul_f32_e32 v192, v169, v192
	v_cvt_pk_bf16_f32 v192, v192, s0
	global_store_short v[194:195], v192, off offset:32
	v_mul_f32_e32 v192, v74, v161
	v_mul_f32_e32 v161, v42, v161
	v_mul_f32_e32 v161, v171, v161
	v_cvt_pk_bf16_f32 v161, v161, s0
	v_cmp_gt_f32_e32 vcc, s93, v196
	global_store_short v[194:195], v161, off offset:96
	v_mul_f32_e32 v161, 0x4b800000, v196
	v_cndmask_b32_e32 v161, v196, v161, vcc
	v_rsq_f32_e32 v161, v161
	v_mul_f32_e32 v192, v170, v192
	v_cvt_pk_bf16_f32 v192, v192, s0
	global_store_short v[194:195], v192, off offset:64
	v_mul_f32_e32 v192, 0x45800000, v161
	v_cndmask_b32_e32 v161, v161, v192, vcc
	v_or_b32_e32 v194, 17, v160
	v_ashrrev_i32_e32 v195, 31, v194
	v_mul_f32_e32 v192, v123, v161
	v_lshlrev_b64 v[194:195], 12, v[194:195]
	v_mul_f32_e32 v192, v168, v192
	v_lshl_add_u64 v[194:195], v[158:159], 0, v[194:195]
	v_cvt_pk_bf16_f32 v192, v192, s0
	global_store_short v[194:195], v192, off
	v_mul_f32_e32 v192, v107, v161
	v_mul_f32_e32 v192, v169, v192
	v_cvt_pk_bf16_f32 v192, v192, s0
	global_store_short v[194:195], v192, off offset:32
	v_mul_f32_e32 v192, v75, v161
	v_mul_f32_e32 v161, v43, v161
	v_mul_f32_e32 v192, v170, v192
	v_mul_f32_e32 v161, v171, v161
	v_cvt_pk_bf16_f32 v192, v192, s0
	v_cvt_pk_bf16_f32 v161, v161, s0
	global_store_short v[194:195], v192, off offset:64
	global_store_short v[194:195], v161, off offset:96
	v_mov_b32_e32 v194, v124
	v_mov_b32_e32 v195, v108
	v_mov_b32_e32 v200, v125
	v_mov_b32_e32 v201, v109
	v_pk_mul_f32 v[194:195], v[194:195], v[194:195]
	v_mov_b32_e32 v196, v76
	v_mov_b32_e32 v197, v44
	v_pk_mul_f32 v[200:201], v[200:201], v[200:201]
	v_mov_b32_e32 v203, v45
	v_pk_mul_f32 v[196:197], v[196:197], v[196:197]
	v_pk_mul_f32 v[202:203], v[202:203], v[202:203]
	v_mov_b32_e32 v204, v200
	v_mov_b32_e32 v205, v194
	v_mov_b32_e32 v194, v201
	v_pk_add_f32 v[194:195], v[204:205], v[194:195]
	v_mov_b32_e32 v200, v202
	v_mov_b32_e32 v201, v196
	v_pk_add_f32 v[194:195], v[194:195], v[200:201]
	v_mov_b32_e32 v196, v203
	v_pk_add_f32 v[194:195], v[194:195], v[196:197]
	ds_bpermute_b32 v197, v175, v195
	ds_bpermute_b32 v196, v175, v194
	v_or_b32_e32 v198, 18, v160
	v_ashrrev_i32_e32 v199, 31, v198
	v_lshlrev_b64 v[198:199], 12, v[198:199]
	v_lshl_add_u64 v[198:199], v[158:159], 0, v[198:199]
	s_waitcnt lgkmcnt(0)
	v_pk_add_f32 v[194:195], v[194:195], v[196:197]
	ds_bpermute_b32 v197, v174, v195
	ds_bpermute_b32 v196, v174, v194
	v_mov_b32_e32 v200, v119
	v_mov_b32_e32 v201, v103
	v_pk_mul_f32 v[200:201], v[200:201], v[200:201]
	v_mov_b32_e32 v202, v67
	s_waitcnt lgkmcnt(0)
	v_pk_add_f32 v[194:195], v[194:195], v[196:197]
	ds_bpermute_b32 v197, v173, v195
	ds_bpermute_b32 v196, v173, v194
	v_mov_b32_e32 v203, v39
	v_pk_mul_f32 v[202:203], v[202:203], v[202:203]
	v_mov_b32_e32 v204, v200
	v_mov_b32_e32 v200, v202
	s_waitcnt lgkmcnt(0)
	v_pk_add_f32 v[194:195], v[194:195], v[196:197]
	ds_bpermute_b32 v197, v172, v195
	ds_bpermute_b32 v196, v172, v194
	v_mov_b32_e32 v202, v69
	s_waitcnt lgkmcnt(0)
	v_pk_add_f32 v[194:195], v[194:195], v[196:197]
	s_nop 0
	v_pk_fma_f32 v[194:195], v[194:195], s[8:9], v[162:163] op_sel_hi:[1,0,0]
	v_mov_b32_e32 v196, v118
	v_mul_f32_e32 v161, 0x4b800000, v195
	v_cmp_gt_f32_e64 s[46:47], s93, v195
	v_mov_b32_e32 v197, v102
	v_pk_mul_f32 v[196:197], v[196:197], v[196:197]
	v_cndmask_b32_e64 v161, v195, v161, s[46:47]
	v_rsq_f32_e32 v161, v161
	v_mov_b32_e32 v205, v196
	v_mov_b32_e32 v196, v201
	v_pk_add_f32 v[196:197], v[204:205], v[196:197]
	v_mul_f32_e32 v192, 0x45800000, v161
	v_cndmask_b32_e64 v161, v161, v192, s[46:47]
	v_mul_f32_e32 v192, v124, v161
	v_mul_f32_e32 v192, v168, v192
	v_cvt_pk_bf16_f32 v192, v192, s0
	global_store_short v[198:199], v192, off
	v_mul_f32_e32 v192, v108, v161
	v_mul_f32_e32 v192, v169, v192
	v_cvt_pk_bf16_f32 v192, v192, s0
	global_store_short v[198:199], v192, off offset:32
	v_mul_f32_e32 v192, v76, v161
	v_mul_f32_e32 v161, v44, v161
	v_mul_f32_e32 v192, v170, v192
	v_mul_f32_e32 v161, v171, v161
	v_cvt_pk_bf16_f32 v192, v192, s0
	v_cvt_pk_bf16_f32 v161, v161, s0
	global_store_short v[198:199], v192, off offset:64
	global_store_short v[198:199], v161, off offset:96
	v_mov_b32_e32 v198, v66
	v_mov_b32_e32 v199, v38
	v_pk_mul_f32 v[198:199], v[198:199], v[198:199]
	v_cmp_gt_f32_e32 vcc, s93, v194
	v_mov_b32_e32 v201, v198
	v_pk_add_f32 v[196:197], v[196:197], v[200:201]
	v_mov_b32_e32 v198, v203
	v_pk_add_f32 v[196:197], v[196:197], v[198:199]
	ds_bpermute_b32 v199, v175, v197
	ds_bpermute_b32 v198, v175, v196
	v_mul_f32_e32 v161, 0x4b800000, v194
	v_cndmask_b32_e32 v161, v194, v161, vcc
	v_rsq_f32_e32 v161, v161
	v_or_b32_e32 v194, 19, v160
	s_waitcnt lgkmcnt(0)
; __device__ __forceinline__ unsigned f2bf(float f) { const __bf16 b = (__bf16)f; return (unsigned)__builtin_bit_cast(unsigned short, b); }
;     __device__ __forceinline__ void operator()(Acc& acc, int pm, int pn, int wr, int wc, int fr, int fq) const {
;     ...
;                     float ss = acc[ai][0][m][0][j] * acc[ai][0][m][0][j] + acc[ai][0][m][1][j] * acc[ai][0][m][1][j] +
;                                acc[ai][1][m][0][j] * acc[ai][1][m][0][j] + acc[ai][1][m][1][j] * acc[ai][1][m][1][j];
;                     ss += __shfl_xor(ss, 1); ss += __shfl_xor(ss, 2); ss += __shfl_xor(ss, 4); ss += __shfl_xor(ss, 8);
;                     const float rs = rsqrtf(ss * (1.0f / 64.0f) + EPSV);
;                     bf16_t* rp = qk + (size_t)(pm * 256 + ai * 128 + wr * 64 + m * 16 + fq * 4 + j) * 2048 + head * 64 + fr;
; #pragma unroll
;                     for (int bj = 0; bj < 2; ++bj)
; #pragma unroll
;                         for (int n = 0; n < 2; ++n) rp[bj * 32 + n * 16] = (bf16_t)f2bf(acc[ai][bj][m][n][j] * rs * gv[bj][n]);
;                 }
	v_pk_add_f32 v[196:197], v[196:197], v[198:199]
	ds_bpermute_b32 v199, v174, v197
	ds_bpermute_b32 v198, v174, v196
	v_mul_f32_e32 v192, 0x45800000, v161
	v_cndmask_b32_e32 v161, v161, v192, vcc
	v_ashrrev_i32_e32 v195, 31, v194
	v_mul_f32_e32 v192, v125, v161
	s_waitcnt lgkmcnt(0)
	v_pk_add_f32 v[196:197], v[196:197], v[198:199]
	ds_bpermute_b32 v199, v173, v197
	ds_bpermute_b32 v198, v173, v196
	v_lshlrev_b64 v[194:195], 12, v[194:195]
	v_mul_f32_e32 v192, v168, v192
	v_lshl_add_u64 v[194:195], v[158:159], 0, v[194:195]
	v_cvt_pk_bf16_f32 v192, v192, s0
	s_waitcnt lgkmcnt(0)
	v_pk_add_f32 v[196:197], v[196:197], v[198:199]
	ds_bpermute_b32 v199, v172, v197
	ds_bpermute_b32 v198, v172, v196
	global_store_short v[194:195], v192, off
	v_mul_f32_e32 v192, v109, v161
	v_mul_f32_e32 v192, v169, v192
	v_cvt_pk_bf16_f32 v192, v192, s0
	global_store_short v[194:195], v192, off offset:32
	v_mul_f32_e32 v192, v77, v161
	v_mul_f32_e32 v161, v45, v161
	v_mul_f32_e32 v161, v171, v161
	s_waitcnt lgkmcnt(0)
	v_pk_add_f32 v[196:197], v[196:197], v[198:199]
	v_cvt_pk_bf16_f32 v161, v161, s0
	v_pk_fma_f32 v[196:197], v[196:197], s[8:9], v[162:163] op_sel_hi:[1,0,0]
	global_store_short v[194:195], v161, off offset:96
	v_mul_f32_e32 v161, 0x4b800000, v197
	v_cmp_gt_f32_e64 s[46:47], s93, v197
	v_mul_f32_e32 v192, v170, v192
	v_cvt_pk_bf16_f32 v192, v192, s0
	v_cndmask_b32_e64 v161, v197, v161, s[46:47]
	v_rsq_f32_e32 v161, v161
	global_store_short v[194:195], v192, off offset:64
	v_or_b32_e32 v194, 32, v160
	v_ashrrev_i32_e32 v195, 31, v194
	v_mul_f32_e32 v192, 0x45800000, v161
	v_cndmask_b32_e64 v161, v161, v192, s[46:47]
	v_mul_f32_e32 v192, v118, v161
	v_lshlrev_b64 v[194:195], 12, v[194:195]
	v_mul_f32_e32 v192, v168, v192
	v_lshl_add_u64 v[194:195], v[158:159], 0, v[194:195]
	v_cvt_pk_bf16_f32 v192, v192, s0
	global_store_short v[194:195], v192, off
	v_mul_f32_e32 v192, v102, v161
	v_mul_f32_e32 v192, v169, v192
	v_cvt_pk_bf16_f32 v192, v192, s0
	global_store_short v[194:195], v192, off offset:32
	v_mul_f32_e32 v192, v66, v161
	v_mul_f32_e32 v161, v38, v161
	v_mul_f32_e32 v161, v171, v161
	v_cvt_pk_bf16_f32 v161, v161, s0
	v_cmp_gt_f32_e32 vcc, s93, v196
	global_store_short v[194:195], v161, off offset:96
	v_mul_f32_e32 v161, 0x4b800000, v196
	v_cndmask_b32_e32 v161, v196, v161, vcc
	v_rsq_f32_e32 v161, v161
	v_mul_f32_e32 v192, v170, v192
	v_cvt_pk_bf16_f32 v192, v192, s0
	global_store_short v[194:195], v192, off offset:64
	v_mul_f32_e32 v192, 0x45800000, v161
	v_cndmask_b32_e32 v161, v161, v192, vcc
	v_or_b32_e32 v194, 33, v160
	v_ashrrev_i32_e32 v195, 31, v194
	v_mul_f32_e32 v192, v119, v161
	v_lshlrev_b64 v[194:195], 12, v[194:195]
	v_mul_f32_e32 v192, v168, v192
	v_lshl_add_u64 v[194:195], v[158:159], 0, v[194:195]
	v_cvt_pk_bf16_f32 v192, v192, s0
	global_store_short v[194:195], v192, off
	v_mul_f32_e32 v192, v103, v161
	v_mul_f32_e32 v192, v169, v192
	v_cvt_pk_bf16_f32 v192, v192, s0
	global_store_short v[194:195], v192, off offset:32
	v_mul_f32_e32 v192, v67, v161
	v_mul_f32_e32 v161, v39, v161
	v_mul_f32_e32 v192, v170, v192
	v_mul_f32_e32 v161, v171, v161
	v_cvt_pk_bf16_f32 v192, v192, s0
	v_cvt_pk_bf16_f32 v161, v161, s0
	global_store_short v[194:195], v192, off offset:64
	global_store_short v[194:195], v161, off offset:96
	v_mov_b32_e32 v194, v120
	v_mov_b32_e32 v195, v104
	v_mov_b32_e32 v200, v121
	v_mov_b32_e32 v201, v105
	v_pk_mul_f32 v[194:195], v[194:195], v[194:195]
	v_mov_b32_e32 v196, v68
	v_mov_b32_e32 v197, v40
	v_pk_mul_f32 v[200:201], v[200:201], v[200:201]
	v_mov_b32_e32 v203, v41
	v_pk_mul_f32 v[196:197], v[196:197], v[196:197]
	v_pk_mul_f32 v[202:203], v[202:203], v[202:203]
	v_mov_b32_e32 v204, v200
	v_mov_b32_e32 v205, v194
	v_mov_b32_e32 v194, v201
	v_pk_add_f32 v[194:195], v[204:205], v[194:195]
	v_mov_b32_e32 v200, v202
	v_mov_b32_e32 v201, v196
	v_pk_add_f32 v[194:195], v[194:195], v[200:201]
	v_mov_b32_e32 v196, v203
	v_pk_add_f32 v[194:195], v[194:195], v[196:197]
	ds_bpermute_b32 v197, v175, v195
	ds_bpermute_b32 v196, v175, v194
	v_or_b32_e32 v198, 34, v160
	v_ashrrev_i32_e32 v199, 31, v198
	v_lshlrev_b64 v[198:199], 12, v[198:199]
	v_lshl_add_u64 v[198:199], v[158:159], 0, v[198:199]
	s_waitcnt lgkmcnt(0)
	v_pk_add_f32 v[194:195], v[194:195], v[196:197]
	ds_bpermute_b32 v197, v174, v195
	ds_bpermute_b32 v196, v174, v194
	v_mov_b32_e32 v200, v115
	v_mov_b32_e32 v201, v95
	v_pk_mul_f32 v[200:201], v[200:201], v[200:201]
	v_mov_b32_e32 v202, v59
	s_waitcnt lgkmcnt(0)
	v_pk_add_f32 v[194:195], v[194:195], v[196:197]
	ds_bpermute_b32 v197, v173, v195
	ds_bpermute_b32 v196, v173, v194
	v_mov_b32_e32 v203, v31
	v_pk_mul_f32 v[202:203], v[202:203], v[202:203]
	v_mov_b32_e32 v204, v200
	v_mov_b32_e32 v200, v202
	s_waitcnt lgkmcnt(0)
	v_pk_add_f32 v[194:195], v[194:195], v[196:197]
	ds_bpermute_b32 v197, v172, v195
	ds_bpermute_b32 v196, v172, v194
	v_mov_b32_e32 v202, v61
	s_waitcnt lgkmcnt(0)
; __device__ __forceinline__ unsigned f2bf(float f) { const __bf16 b = (__bf16)f; return (unsigned)__builtin_bit_cast(unsigned short, b); }
;     __device__ __forceinline__ void operator()(Acc& acc, int pm, int pn, int wr, int wc, int fr, int fq) const {
;     ...
;                     float ss = acc[ai][0][m][0][j] * acc[ai][0][m][0][j] + acc[ai][0][m][1][j] * acc[ai][0][m][1][j] +
;                                acc[ai][1][m][0][j] * acc[ai][1][m][0][j] + acc[ai][1][m][1][j] * acc[ai][1][m][1][j];
;                     ss += __shfl_xor(ss, 1); ss += __shfl_xor(ss, 2); ss += __shfl_xor(ss, 4); ss += __shfl_xor(ss, 8);
;                     const float rs = rsqrtf(ss * (1.0f / 64.0f) + EPSV);
;                     bf16_t* rp = qk + (size_t)(pm * 256 + ai * 128 + wr * 64 + m * 16 + fq * 4 + j) * 2048 + head * 64 + fr;
; #pragma unroll
;                     for (int bj = 0; bj < 2; ++bj)
; #pragma unroll
;                         for (int n = 0; n < 2; ++n) rp[bj * 32 + n * 16] = (bf16_t)f2bf(acc[ai][bj][m][n][j] * rs * gv[bj][n]);
;                 }
	v_pk_add_f32 v[194:195], v[194:195], v[196:197]
	s_nop 0
	v_pk_fma_f32 v[194:195], v[194:195], s[8:9], v[162:163] op_sel_hi:[1,0,0]
	v_mov_b32_e32 v196, v114
	v_mul_f32_e32 v161, 0x4b800000, v195
	v_cmp_gt_f32_e64 s[46:47], s93, v195
	v_mov_b32_e32 v197, v94
	v_pk_mul_f32 v[196:197], v[196:197], v[196:197]
	v_cndmask_b32_e64 v161, v195, v161, s[46:47]
	v_rsq_f32_e32 v161, v161
	v_mov_b32_e32 v205, v196
	v_mov_b32_e32 v196, v201
	v_pk_add_f32 v[196:197], v[204:205], v[196:197]
	v_mul_f32_e32 v192, 0x45800000, v161
	v_cndmask_b32_e64 v161, v161, v192, s[46:47]
	v_mul_f32_e32 v192, v120, v161
	v_mul_f32_e32 v192, v168, v192
	v_cvt_pk_bf16_f32 v192, v192, s0
	global_store_short v[198:199], v192, off
	v_mul_f32_e32 v192, v104, v161
	v_mul_f32_e32 v192, v169, v192
	v_cvt_pk_bf16_f32 v192, v192, s0
	global_store_short v[198:199], v192, off offset:32
	v_mul_f32_e32 v192, v68, v161
	v_mul_f32_e32 v161, v40, v161
	v_mul_f32_e32 v192, v170, v192
	v_mul_f32_e32 v161, v171, v161
	v_cvt_pk_bf16_f32 v192, v192, s0
	v_cvt_pk_bf16_f32 v161, v161, s0
	global_store_short v[198:199], v192, off offset:64
	global_store_short v[198:199], v161, off offset:96
	v_mov_b32_e32 v198, v58
	v_mov_b32_e32 v199, v30
	v_pk_mul_f32 v[198:199], v[198:199], v[198:199]
	v_cmp_gt_f32_e32 vcc, s93, v194
	v_mov_b32_e32 v201, v198
	v_pk_add_f32 v[196:197], v[196:197], v[200:201]
	v_mov_b32_e32 v198, v203
	v_pk_add_f32 v[196:197], v[196:197], v[198:199]
	ds_bpermute_b32 v199, v175, v197
	ds_bpermute_b32 v198, v175, v196
	v_mul_f32_e32 v161, 0x4b800000, v194
	v_cndmask_b32_e32 v161, v194, v161, vcc
	v_rsq_f32_e32 v161, v161
	v_or_b32_e32 v194, 35, v160
	s_waitcnt lgkmcnt(0)
	v_pk_add_f32 v[196:197], v[196:197], v[198:199]
	ds_bpermute_b32 v199, v174, v197
	ds_bpermute_b32 v198, v174, v196
	v_mul_f32_e32 v192, 0x45800000, v161
	v_cndmask_b32_e32 v161, v161, v192, vcc
	v_ashrrev_i32_e32 v195, 31, v194
	v_mul_f32_e32 v192, v121, v161
	s_waitcnt lgkmcnt(0)
	v_pk_add_f32 v[196:197], v[196:197], v[198:199]
	ds_bpermute_b32 v199, v173, v197
	ds_bpermute_b32 v198, v173, v196
	v_lshlrev_b64 v[194:195], 12, v[194:195]
	v_mul_f32_e32 v192, v168, v192
	v_lshl_add_u64 v[194:195], v[158:159], 0, v[194:195]
	v_cvt_pk_bf16_f32 v192, v192, s0
	s_waitcnt lgkmcnt(0)
	v_pk_add_f32 v[196:197], v[196:197], v[198:199]
	ds_bpermute_b32 v199, v172, v197
	ds_bpermute_b32 v198, v172, v196
	global_store_short v[194:195], v192, off
	v_mul_f32_e32 v192, v105, v161
	v_mul_f32_e32 v192, v169, v192
	v_cvt_pk_bf16_f32 v192, v192, s0
	global_store_short v[194:195], v192, off offset:32
	v_mul_f32_e32 v192, v69, v161
	v_mul_f32_e32 v161, v41, v161
	v_mul_f32_e32 v161, v171, v161
	s_waitcnt lgkmcnt(0)
	v_pk_add_f32 v[196:197], v[196:197], v[198:199]
	v_cvt_pk_bf16_f32 v161, v161, s0
	v_pk_fma_f32 v[196:197], v[196:197], s[8:9], v[162:163] op_sel_hi:[1,0,0]
	global_store_short v[194:195], v161, off offset:96
	v_mul_f32_e32 v161, 0x4b800000, v197
	v_cmp_gt_f32_e64 s[46:47], s93, v197
	v_mul_f32_e32 v192, v170, v192
	v_cvt_pk_bf16_f32 v192, v192, s0
	v_cndmask_b32_e64 v161, v197, v161, s[46:47]
	v_rsq_f32_e32 v161, v161
	global_store_short v[194:195], v192, off offset:64
	v_or_b32_e32 v194, 48, v160
	v_ashrrev_i32_e32 v195, 31, v194
	v_mul_f32_e32 v192, 0x45800000, v161
	v_cndmask_b32_e64 v161, v161, v192, s[46:47]
	v_mul_f32_e32 v192, v114, v161
	v_lshlrev_b64 v[194:195], 12, v[194:195]
	v_mul_f32_e32 v192, v168, v192
	v_lshl_add_u64 v[194:195], v[158:159], 0, v[194:195]
	v_cvt_pk_bf16_f32 v192, v192, s0
	global_store_short v[194:195], v192, off
	v_mul_f32_e32 v192, v94, v161
	v_mul_f32_e32 v192, v169, v192
	v_cvt_pk_bf16_f32 v192, v192, s0
	global_store_short v[194:195], v192, off offset:32
	v_mul_f32_e32 v192, v58, v161
	v_mul_f32_e32 v161, v30, v161
	v_mul_f32_e32 v161, v171, v161
	v_cvt_pk_bf16_f32 v161, v161, s0
	v_cmp_gt_f32_e32 vcc, s93, v196
	global_store_short v[194:195], v161, off offset:96
	v_mul_f32_e32 v161, 0x4b800000, v196
	v_cndmask_b32_e32 v161, v196, v161, vcc
	v_rsq_f32_e32 v161, v161
	v_mul_f32_e32 v192, v170, v192
	v_cvt_pk_bf16_f32 v192, v192, s0
	global_store_short v[194:195], v192, off offset:64
	v_mul_f32_e32 v192, 0x45800000, v161
	v_cndmask_b32_e32 v161, v161, v192, vcc
	v_or_b32_e32 v194, 49, v160
	v_ashrrev_i32_e32 v195, 31, v194
	v_mul_f32_e32 v192, v115, v161
	v_lshlrev_b64 v[194:195], 12, v[194:195]
	v_mul_f32_e32 v192, v168, v192
	v_lshl_add_u64 v[194:195], v[158:159], 0, v[194:195]
	v_cvt_pk_bf16_f32 v192, v192, s0
	global_store_short v[194:195], v192, off
	v_mul_f32_e32 v192, v95, v161
	v_mul_f32_e32 v192, v169, v192
	v_cvt_pk_bf16_f32 v192, v192, s0
	global_store_short v[194:195], v192, off offset:32
	v_mul_f32_e32 v192, v59, v161
	v_mul_f32_e32 v161, v31, v161
	v_mul_f32_e32 v192, v170, v192
	v_mul_f32_e32 v161, v171, v161
	v_cvt_pk_bf16_f32 v192, v192, s0
	v_cvt_pk_bf16_f32 v161, v161, s0
	global_store_short v[194:195], v192, off offset:64
	global_store_short v[194:195], v161, off offset:96
	v_mov_b32_e32 v194, v116
	v_mov_b32_e32 v195, v96
	v_mov_b32_e32 v200, v117
	v_mov_b32_e32 v201, v97
	v_pk_mul_f32 v[194:195], v[194:195], v[194:195]
	v_mov_b32_e32 v196, v60
	v_mov_b32_e32 v197, v32
	v_pk_mul_f32 v[200:201], v[200:201], v[200:201]
	v_mov_b32_e32 v203, v33
	v_pk_mul_f32 v[196:197], v[196:197], v[196:197]
	v_pk_mul_f32 v[202:203], v[202:203], v[202:203]
	v_mov_b32_e32 v204, v200
	v_mov_b32_e32 v205, v194
	v_mov_b32_e32 v194, v201
	v_pk_add_f32 v[194:195], v[204:205], v[194:195]
	v_mov_b32_e32 v200, v202
	v_mov_b32_e32 v201, v196
	v_pk_add_f32 v[194:195], v[194:195], v[200:201]
	v_mov_b32_e32 v196, v203
	v_pk_add_f32 v[194:195], v[194:195], v[196:197]
	ds_bpermute_b32 v197, v175, v195
	ds_bpermute_b32 v196, v175, v194
	v_or_b32_e32 v198, 50, v160
	v_ashrrev_i32_e32 v199, 31, v198
	v_lshlrev_b64 v[198:199], 12, v[198:199]
	v_lshl_add_u64 v[198:199], v[158:159], 0, v[198:199]
	s_waitcnt lgkmcnt(0)
; __device__ __forceinline__ unsigned f2bf(float f) { const __bf16 b = (__bf16)f; return (unsigned)__builtin_bit_cast(unsigned short, b); }
;     __device__ __forceinline__ void operator()(Acc& acc, int pm, int pn, int wr, int wc, int fr, int fq) const {
;     ...
;                     float ss = acc[ai][0][m][0][j] * acc[ai][0][m][0][j] + acc[ai][0][m][1][j] * acc[ai][0][m][1][j] +
;                                acc[ai][1][m][0][j] * acc[ai][1][m][0][j] + acc[ai][1][m][1][j] * acc[ai][1][m][1][j];
;                     ss += __shfl_xor(ss, 1); ss += __shfl_xor(ss, 2); ss += __shfl_xor(ss, 4); ss += __shfl_xor(ss, 8);
;                     const float rs = rsqrtf(ss * (1.0f / 64.0f) + EPSV);
;                     bf16_t* rp = qk + (size_t)(pm * 256 + ai * 128 + wr * 64 + m * 16 + fq * 4 + j) * 2048 + head * 64 + fr;
; #pragma unroll
;                     for (int bj = 0; bj < 2; ++bj)
; #pragma unroll
;                         for (int n = 0; n < 2; ++n) rp[bj * 32 + n * 16] = (bf16_t)f2bf(acc[ai][bj][m][n][j] * rs * gv[bj][n]);
;                 }
	v_pk_add_f32 v[194:195], v[194:195], v[196:197]
	ds_bpermute_b32 v197, v174, v195
	ds_bpermute_b32 v196, v174, v194
	v_mov_b32_e32 v200, v99
	v_mov_b32_e32 v201, v71
	v_pk_mul_f32 v[200:201], v[200:201], v[200:201]
	v_mov_b32_e32 v202, v35
	s_waitcnt lgkmcnt(0)
	v_pk_add_f32 v[194:195], v[194:195], v[196:197]
	ds_bpermute_b32 v197, v173, v195
	ds_bpermute_b32 v196, v173, v194
	v_mov_b32_e32 v203, v15
	v_pk_mul_f32 v[202:203], v[202:203], v[202:203]
	v_mov_b32_e32 v204, v200
	v_mov_b32_e32 v200, v202
	s_waitcnt lgkmcnt(0)
	v_pk_add_f32 v[194:195], v[194:195], v[196:197]
	ds_bpermute_b32 v197, v172, v195
	ds_bpermute_b32 v196, v172, v194
	v_mov_b32_e32 v202, v37
	s_waitcnt lgkmcnt(0)
	v_pk_add_f32 v[194:195], v[194:195], v[196:197]
	s_nop 0
	v_pk_fma_f32 v[194:195], v[194:195], s[8:9], v[162:163] op_sel_hi:[1,0,0]
	v_mov_b32_e32 v196, v98
	v_mul_f32_e32 v161, 0x4b800000, v195
	v_cmp_gt_f32_e64 s[46:47], s93, v195
	v_mov_b32_e32 v197, v70
	v_pk_mul_f32 v[196:197], v[196:197], v[196:197]
	v_cndmask_b32_e64 v161, v195, v161, s[46:47]
	v_rsq_f32_e32 v161, v161
	v_mov_b32_e32 v205, v196
	v_mov_b32_e32 v196, v201
	v_pk_add_f32 v[196:197], v[204:205], v[196:197]
	v_mul_f32_e32 v192, 0x45800000, v161
	v_cndmask_b32_e64 v161, v161, v192, s[46:47]
	v_mul_f32_e32 v192, v116, v161
	v_mul_f32_e32 v192, v168, v192
	v_cvt_pk_bf16_f32 v192, v192, s0
	global_store_short v[198:199], v192, off
	v_mul_f32_e32 v192, v96, v161
	v_mul_f32_e32 v192, v169, v192
	v_cvt_pk_bf16_f32 v192, v192, s0
	global_store_short v[198:199], v192, off offset:32
	v_mul_f32_e32 v192, v60, v161
	v_mul_f32_e32 v161, v32, v161
	v_mul_f32_e32 v192, v170, v192
	v_mul_f32_e32 v161, v171, v161
	v_cvt_pk_bf16_f32 v192, v192, s0
	v_cvt_pk_bf16_f32 v161, v161, s0
	global_store_short v[198:199], v192, off offset:64
	global_store_short v[198:199], v161, off offset:96
	v_mov_b32_e32 v198, v34
	v_mov_b32_e32 v199, v14
	v_pk_mul_f32 v[198:199], v[198:199], v[198:199]
	v_cmp_gt_f32_e32 vcc, s93, v194
	v_mov_b32_e32 v201, v198
	v_pk_add_f32 v[196:197], v[196:197], v[200:201]
	v_mov_b32_e32 v198, v203
	v_pk_add_f32 v[196:197], v[196:197], v[198:199]
	ds_bpermute_b32 v199, v175, v197
	ds_bpermute_b32 v198, v175, v196
	v_mul_f32_e32 v161, 0x4b800000, v194
	v_cndmask_b32_e32 v161, v194, v161, vcc
	v_rsq_f32_e32 v161, v161
	v_or_b32_e32 v194, 51, v160
	s_waitcnt lgkmcnt(0)
	v_pk_add_f32 v[196:197], v[196:197], v[198:199]
	ds_bpermute_b32 v199, v174, v197
	ds_bpermute_b32 v198, v174, v196
	v_mul_f32_e32 v192, 0x45800000, v161
	v_cndmask_b32_e32 v161, v161, v192, vcc
	v_ashrrev_i32_e32 v195, 31, v194
	v_mul_f32_e32 v192, v117, v161
	s_waitcnt lgkmcnt(0)
	v_pk_add_f32 v[196:197], v[196:197], v[198:199]
	ds_bpermute_b32 v199, v173, v197
	ds_bpermute_b32 v198, v173, v196
	v_lshlrev_b64 v[194:195], 12, v[194:195]
	v_mul_f32_e32 v192, v168, v192
	v_lshl_add_u64 v[194:195], v[158:159], 0, v[194:195]
	v_cvt_pk_bf16_f32 v192, v192, s0
	s_waitcnt lgkmcnt(0)
	v_pk_add_f32 v[196:197], v[196:197], v[198:199]
	ds_bpermute_b32 v199, v172, v197
	ds_bpermute_b32 v198, v172, v196
	global_store_short v[194:195], v192, off
	v_mul_f32_e32 v192, v97, v161
	v_mul_f32_e32 v192, v169, v192
	v_cvt_pk_bf16_f32 v192, v192, s0
	global_store_short v[194:195], v192, off offset:32
	v_mul_f32_e32 v192, v61, v161
	v_mul_f32_e32 v161, v33, v161
	v_mul_f32_e32 v161, v171, v161
	s_waitcnt lgkmcnt(0)
	v_pk_add_f32 v[196:197], v[196:197], v[198:199]
	v_cvt_pk_bf16_f32 v161, v161, s0
	v_pk_fma_f32 v[196:197], v[196:197], s[8:9], v[162:163] op_sel_hi:[1,0,0]
	global_store_short v[194:195], v161, off offset:96
	v_mul_f32_e32 v161, 0x4b800000, v197
	v_cmp_gt_f32_e64 s[46:47], s93, v197
	v_mul_f32_e32 v192, v170, v192
	v_cvt_pk_bf16_f32 v192, v192, s0
	v_cndmask_b32_e64 v161, v197, v161, s[46:47]
	v_rsq_f32_e32 v161, v161
	global_store_short v[194:195], v192, off offset:64
	v_add_u32_e32 v194, 0x80, v160
	v_ashrrev_i32_e32 v195, 31, v194
	v_mul_f32_e32 v192, 0x45800000, v161
	v_cndmask_b32_e64 v161, v161, v192, s[46:47]
	v_mul_f32_e32 v192, v98, v161
	v_lshlrev_b64 v[194:195], 12, v[194:195]
	v_mul_f32_e32 v192, v168, v192
	v_lshl_add_u64 v[194:195], v[158:159], 0, v[194:195]
	v_cvt_pk_bf16_f32 v192, v192, s0
	global_store_short v[194:195], v192, off
	v_mul_f32_e32 v192, v70, v161
	v_mul_f32_e32 v192, v169, v192
	v_cvt_pk_bf16_f32 v192, v192, s0
	global_store_short v[194:195], v192, off offset:32
	v_mul_f32_e32 v192, v34, v161
	v_mul_f32_e32 v161, v14, v161
	v_mul_f32_e32 v161, v171, v161
	v_cvt_pk_bf16_f32 v161, v161, s0
	v_cmp_gt_f32_e32 vcc, s93, v196
	global_store_short v[194:195], v161, off offset:96
	v_mul_f32_e32 v161, 0x4b800000, v196
	v_cndmask_b32_e32 v161, v196, v161, vcc
	v_rsq_f32_e32 v161, v161
	v_mul_f32_e32 v192, v170, v192
	v_cvt_pk_bf16_f32 v192, v192, s0
	global_store_short v[194:195], v192, off offset:64
	v_mul_f32_e32 v192, 0x45800000, v161
	v_cndmask_b32_e32 v161, v161, v192, vcc
	v_add_u32_e32 v194, 0x81, v160
	v_ashrrev_i32_e32 v195, 31, v194
	v_mul_f32_e32 v192, v99, v161
	v_lshlrev_b64 v[194:195], 12, v[194:195]
	v_mul_f32_e32 v192, v168, v192
	v_lshl_add_u64 v[194:195], v[158:159], 0, v[194:195]
	v_cvt_pk_bf16_f32 v192, v192, s0
	global_store_short v[194:195], v192, off
	v_mul_f32_e32 v192, v71, v161
	v_mul_f32_e32 v192, v169, v192
	v_cvt_pk_bf16_f32 v192, v192, s0
	global_store_short v[194:195], v192, off offset:32
	v_mul_f32_e32 v192, v35, v161
	v_mul_f32_e32 v161, v15, v161
	v_mul_f32_e32 v192, v170, v192
	v_mul_f32_e32 v161, v171, v161
	v_cvt_pk_bf16_f32 v192, v192, s0
	v_cvt_pk_bf16_f32 v161, v161, s0
	global_store_short v[194:195], v192, off offset:64
	global_store_short v[194:195], v161, off offset:96
	v_mov_b32_e32 v194, v100
	v_mov_b32_e32 v195, v72
	v_mov_b32_e32 v200, v101
	v_mov_b32_e32 v201, v73
	v_pk_mul_f32 v[194:195], v[194:195], v[194:195]
	v_mov_b32_e32 v196, v36
	v_mov_b32_e32 v197, v16
	v_pk_mul_f32 v[200:201], v[200:201], v[200:201]
	v_mov_b32_e32 v203, v17
	v_pk_mul_f32 v[196:197], v[196:197], v[196:197]
	v_pk_mul_f32 v[202:203], v[202:203], v[202:203]
	v_mov_b32_e32 v204, v200
	v_mov_b32_e32 v205, v194
	v_mov_b32_e32 v194, v201
	v_pk_add_f32 v[194:195], v[204:205], v[194:195]
	v_mov_b32_e32 v200, v202
	v_mov_b32_e32 v201, v196
	v_pk_add_f32 v[194:195], v[194:195], v[200:201]
	v_mov_b32_e32 v196, v203
	v_pk_add_f32 v[194:195], v[194:195], v[196:197]
	ds_bpermute_b32 v197, v175, v195
	ds_bpermute_b32 v196, v175, v194
	v_add_u32_e32 v198, 0x82, v160
	v_ashrrev_i32_e32 v199, 31, v198
	v_lshlrev_b64 v[198:199], 12, v[198:199]
	v_lshl_add_u64 v[198:199], v[158:159], 0, v[198:199]
	s_waitcnt lgkmcnt(0)
; __device__ __forceinline__ unsigned f2bf(float f) { const __bf16 b = (__bf16)f; return (unsigned)__builtin_bit_cast(unsigned short, b); }
;     __device__ __forceinline__ void operator()(Acc& acc, int pm, int pn, int wr, int wc, int fr, int fq) const {
;     ...
;                     float ss = acc[ai][0][m][0][j] * acc[ai][0][m][0][j] + acc[ai][0][m][1][j] * acc[ai][0][m][1][j] +
;                                acc[ai][1][m][0][j] * acc[ai][1][m][0][j] + acc[ai][1][m][1][j] * acc[ai][1][m][1][j];
;                     ss += __shfl_xor(ss, 1); ss += __shfl_xor(ss, 2); ss += __shfl_xor(ss, 4); ss += __shfl_xor(ss, 8);
;                     const float rs = rsqrtf(ss * (1.0f / 64.0f) + EPSV);
;                     bf16_t* rp = qk + (size_t)(pm * 256 + ai * 128 + wr * 64 + m * 16 + fq * 4 + j) * 2048 + head * 64 + fr;
; #pragma unroll
;                     for (int bj = 0; bj < 2; ++bj)
; #pragma unroll
;                         for (int n = 0; n < 2; ++n) rp[bj * 32 + n * 16] = (bf16_t)f2bf(acc[ai][bj][m][n][j] * rs * gv[bj][n]);
;                 }
	v_pk_add_f32 v[194:195], v[194:195], v[196:197]
	ds_bpermute_b32 v197, v174, v195
	ds_bpermute_b32 v196, v174, v194
	v_mov_b32_e32 v200, v91
	v_mov_b32_e32 v201, v63
	v_pk_mul_f32 v[200:201], v[200:201], v[200:201]
	v_mov_b32_e32 v202, v27
	s_waitcnt lgkmcnt(0)
	v_pk_add_f32 v[194:195], v[194:195], v[196:197]
	ds_bpermute_b32 v197, v173, v195
	ds_bpermute_b32 v196, v173, v194
	v_mov_b32_e32 v203, v11
	v_pk_mul_f32 v[202:203], v[202:203], v[202:203]
	v_mov_b32_e32 v204, v200
	v_mov_b32_e32 v200, v202
	s_waitcnt lgkmcnt(0)
	v_pk_add_f32 v[194:195], v[194:195], v[196:197]
	ds_bpermute_b32 v197, v172, v195
	ds_bpermute_b32 v196, v172, v194
	v_mov_b32_e32 v202, v29
	s_waitcnt lgkmcnt(0)
	v_pk_add_f32 v[194:195], v[194:195], v[196:197]
	s_nop 0
	v_pk_fma_f32 v[194:195], v[194:195], s[8:9], v[162:163] op_sel_hi:[1,0,0]
	v_mov_b32_e32 v196, v90
	v_mul_f32_e32 v161, 0x4b800000, v195
	v_cmp_gt_f32_e64 s[46:47], s93, v195
	v_mov_b32_e32 v197, v62
	v_pk_mul_f32 v[196:197], v[196:197], v[196:197]
	v_cndmask_b32_e64 v161, v195, v161, s[46:47]
	v_rsq_f32_e32 v161, v161
	v_mov_b32_e32 v205, v196
	v_mov_b32_e32 v196, v201
	v_pk_add_f32 v[196:197], v[204:205], v[196:197]
	v_mul_f32_e32 v192, 0x45800000, v161
	v_cndmask_b32_e64 v161, v161, v192, s[46:47]
	v_mul_f32_e32 v192, v100, v161
	v_mul_f32_e32 v192, v168, v192
	v_cvt_pk_bf16_f32 v192, v192, s0
	global_store_short v[198:199], v192, off
	v_mul_f32_e32 v192, v72, v161
	v_mul_f32_e32 v192, v169, v192
	v_cvt_pk_bf16_f32 v192, v192, s0
	global_store_short v[198:199], v192, off offset:32
	v_mul_f32_e32 v192, v36, v161
	v_mul_f32_e32 v161, v16, v161
	v_mul_f32_e32 v192, v170, v192
	v_mul_f32_e32 v161, v171, v161
	v_cvt_pk_bf16_f32 v192, v192, s0
	v_cvt_pk_bf16_f32 v161, v161, s0
	global_store_short v[198:199], v192, off offset:64
	global_store_short v[198:199], v161, off offset:96
	v_mov_b32_e32 v198, v26
	v_mov_b32_e32 v199, v10
	v_pk_mul_f32 v[198:199], v[198:199], v[198:199]
	v_cmp_gt_f32_e32 vcc, s93, v194
	v_mov_b32_e32 v201, v198
	v_pk_add_f32 v[196:197], v[196:197], v[200:201]
	v_mov_b32_e32 v198, v203
	v_pk_add_f32 v[196:197], v[196:197], v[198:199]
	ds_bpermute_b32 v199, v175, v197
	ds_bpermute_b32 v198, v175, v196
	v_mul_f32_e32 v161, 0x4b800000, v194
	v_cndmask_b32_e32 v161, v194, v161, vcc
	v_rsq_f32_e32 v161, v161
	v_add_u32_e32 v194, 0x83, v160
	s_waitcnt lgkmcnt(0)
	v_pk_add_f32 v[196:197], v[196:197], v[198:199]
	ds_bpermute_b32 v199, v174, v197
	ds_bpermute_b32 v198, v174, v196
	v_mul_f32_e32 v192, 0x45800000, v161
	v_cndmask_b32_e32 v161, v161, v192, vcc
	v_ashrrev_i32_e32 v195, 31, v194
	v_mul_f32_e32 v192, v101, v161
	s_waitcnt lgkmcnt(0)
	v_pk_add_f32 v[196:197], v[196:197], v[198:199]
	ds_bpermute_b32 v199, v173, v197
	ds_bpermute_b32 v198, v173, v196
	v_lshlrev_b64 v[194:195], 12, v[194:195]
	v_mul_f32_e32 v192, v168, v192
	v_lshl_add_u64 v[194:195], v[158:159], 0, v[194:195]
	v_cvt_pk_bf16_f32 v192, v192, s0
	s_waitcnt lgkmcnt(0)
	v_pk_add_f32 v[196:197], v[196:197], v[198:199]
	ds_bpermute_b32 v199, v172, v197
	ds_bpermute_b32 v198, v172, v196
	global_store_short v[194:195], v192, off
	v_mul_f32_e32 v192, v73, v161
	v_mul_f32_e32 v192, v169, v192
	v_cvt_pk_bf16_f32 v192, v192, s0
	global_store_short v[194:195], v192, off offset:32
	v_mul_f32_e32 v192, v37, v161
	v_mul_f32_e32 v161, v17, v161
	v_mul_f32_e32 v161, v171, v161
	s_waitcnt lgkmcnt(0)
	v_pk_add_f32 v[196:197], v[196:197], v[198:199]
	v_cvt_pk_bf16_f32 v161, v161, s0
	v_pk_fma_f32 v[196:197], v[196:197], s[8:9], v[162:163] op_sel_hi:[1,0,0]
	global_store_short v[194:195], v161, off offset:96
	v_mul_f32_e32 v161, 0x4b800000, v197
	v_cmp_gt_f32_e64 s[46:47], s93, v197
	v_mul_f32_e32 v192, v170, v192
	v_cvt_pk_bf16_f32 v192, v192, s0
	v_cndmask_b32_e64 v161, v197, v161, s[46:47]
	v_rsq_f32_e32 v161, v161
	global_store_short v[194:195], v192, off offset:64
	v_add_u32_e32 v194, 0x90, v160
	v_ashrrev_i32_e32 v195, 31, v194
	v_mul_f32_e32 v192, 0x45800000, v161
	v_cndmask_b32_e64 v161, v161, v192, s[46:47]
	v_mul_f32_e32 v192, v90, v161
	v_lshlrev_b64 v[194:195], 12, v[194:195]
	v_mul_f32_e32 v192, v168, v192
	v_lshl_add_u64 v[194:195], v[158:159], 0, v[194:195]
	v_cvt_pk_bf16_f32 v192, v192, s0
	global_store_short v[194:195], v192, off
	v_mul_f32_e32 v192, v62, v161
	v_mul_f32_e32 v192, v169, v192
	v_cvt_pk_bf16_f32 v192, v192, s0
	global_store_short v[194:195], v192, off offset:32
	v_mul_f32_e32 v192, v26, v161
	v_mul_f32_e32 v161, v10, v161
	v_mul_f32_e32 v161, v171, v161
	v_cvt_pk_bf16_f32 v161, v161, s0
	v_cmp_gt_f32_e32 vcc, s93, v196
	global_store_short v[194:195], v161, off offset:96
	v_mul_f32_e32 v161, 0x4b800000, v196
	v_cndmask_b32_e32 v161, v196, v161, vcc
	v_rsq_f32_e32 v161, v161
	v_mul_f32_e32 v192, v170, v192
	v_cvt_pk_bf16_f32 v192, v192, s0
	global_store_short v[194:195], v192, off offset:64
	v_mul_f32_e32 v192, 0x45800000, v161
	v_cndmask_b32_e32 v161, v161, v192, vcc
	v_add_u32_e32 v194, 0x91, v160
	v_ashrrev_i32_e32 v195, 31, v194
	v_mul_f32_e32 v192, v91, v161
	v_lshlrev_b64 v[194:195], 12, v[194:195]
	v_mul_f32_e32 v192, v168, v192
	v_lshl_add_u64 v[194:195], v[158:159], 0, v[194:195]
	v_cvt_pk_bf16_f32 v192, v192, s0
	global_store_short v[194:195], v192, off
	v_mul_f32_e32 v192, v63, v161
	v_mul_f32_e32 v192, v169, v192
	v_cvt_pk_bf16_f32 v192, v192, s0
	global_store_short v[194:195], v192, off offset:32
	v_mul_f32_e32 v192, v27, v161
	v_mul_f32_e32 v161, v11, v161
	v_mul_f32_e32 v192, v170, v192
	v_mul_f32_e32 v161, v171, v161
	v_cvt_pk_bf16_f32 v192, v192, s0
	v_cvt_pk_bf16_f32 v161, v161, s0
	global_store_short v[194:195], v192, off offset:64
	global_store_short v[194:195], v161, off offset:96
	v_mov_b32_e32 v194, v92
	v_mov_b32_e32 v195, v64
	v_mov_b32_e32 v200, v93
	v_mov_b32_e32 v201, v65
	v_pk_mul_f32 v[194:195], v[194:195], v[194:195]
	v_mov_b32_e32 v196, v28
	v_mov_b32_e32 v197, v12
	v_pk_mul_f32 v[200:201], v[200:201], v[200:201]
	v_mov_b32_e32 v203, v13
	v_pk_mul_f32 v[196:197], v[196:197], v[196:197]
	v_pk_mul_f32 v[202:203], v[202:203], v[202:203]
	v_mov_b32_e32 v204, v200
	v_mov_b32_e32 v205, v194
	v_mov_b32_e32 v194, v201
	v_pk_add_f32 v[194:195], v[204:205], v[194:195]
	v_mov_b32_e32 v200, v202
	v_mov_b32_e32 v201, v196
	v_pk_add_f32 v[194:195], v[194:195], v[200:201]
	v_mov_b32_e32 v196, v203
	v_pk_add_f32 v[194:195], v[194:195], v[196:197]
	ds_bpermute_b32 v197, v175, v195
	ds_bpermute_b32 v196, v175, v194
	v_add_u32_e32 v198, 0x92, v160
	v_ashrrev_i32_e32 v199, 31, v198
	v_lshlrev_b64 v[198:199], 12, v[198:199]
	v_lshl_add_u64 v[198:199], v[158:159], 0, v[198:199]
	s_waitcnt lgkmcnt(0)
; __device__ __forceinline__ unsigned f2bf(float f) { const __bf16 b = (__bf16)f; return (unsigned)__builtin_bit_cast(unsigned short, b); }
;     __device__ __forceinline__ void operator()(Acc& acc, int pm, int pn, int wr, int wc, int fr, int fq) const {
;     ...
;                     float ss = acc[ai][0][m][0][j] * acc[ai][0][m][0][j] + acc[ai][0][m][1][j] * acc[ai][0][m][1][j] +
;                                acc[ai][1][m][0][j] * acc[ai][1][m][0][j] + acc[ai][1][m][1][j] * acc[ai][1][m][1][j];
;                     ss += __shfl_xor(ss, 1); ss += __shfl_xor(ss, 2); ss += __shfl_xor(ss, 4); ss += __shfl_xor(ss, 8);
;                     const float rs = rsqrtf(ss * (1.0f / 64.0f) + EPSV);
;                     bf16_t* rp = qk + (size_t)(pm * 256 + ai * 128 + wr * 64 + m * 16 + fq * 4 + j) * 2048 + head * 64 + fr;
; #pragma unroll
;                     for (int bj = 0; bj < 2; ++bj)
; #pragma unroll
;                         for (int n = 0; n < 2; ++n) rp[bj * 32 + n * 16] = (bf16_t)f2bf(acc[ai][bj][m][n][j] * rs * gv[bj][n]);
;                 }
	v_pk_add_f32 v[194:195], v[194:195], v[196:197]
	ds_bpermute_b32 v197, v174, v195
	ds_bpermute_b32 v196, v174, v194
	v_mov_b32_e32 v200, v87
	v_mov_b32_e32 v201, v55
	v_pk_mul_f32 v[200:201], v[200:201], v[200:201]
	v_mov_b32_e32 v202, v23
	s_waitcnt lgkmcnt(0)
	v_pk_add_f32 v[194:195], v[194:195], v[196:197]
	ds_bpermute_b32 v197, v173, v195
	ds_bpermute_b32 v196, v173, v194
	v_mov_b32_e32 v203, v7
	v_pk_mul_f32 v[202:203], v[202:203], v[202:203]
	v_mov_b32_e32 v204, v200
	v_mov_b32_e32 v200, v202
	s_waitcnt lgkmcnt(0)
	v_pk_add_f32 v[194:195], v[194:195], v[196:197]
	ds_bpermute_b32 v197, v172, v195
	ds_bpermute_b32 v196, v172, v194
	v_mov_b32_e32 v202, v25
	s_waitcnt lgkmcnt(0)
	v_pk_add_f32 v[194:195], v[194:195], v[196:197]
	s_nop 0
	v_pk_fma_f32 v[194:195], v[194:195], s[8:9], v[162:163] op_sel_hi:[1,0,0]
	v_mov_b32_e32 v196, v86
	v_mul_f32_e32 v161, 0x4b800000, v195
	v_cmp_gt_f32_e64 s[46:47], s93, v195
	v_mov_b32_e32 v197, v54
	v_pk_mul_f32 v[196:197], v[196:197], v[196:197]
	v_cndmask_b32_e64 v161, v195, v161, s[46:47]
	v_rsq_f32_e32 v161, v161
	v_mov_b32_e32 v205, v196
	v_mov_b32_e32 v196, v201
	v_pk_add_f32 v[196:197], v[204:205], v[196:197]
	v_mul_f32_e32 v192, 0x45800000, v161
	v_cndmask_b32_e64 v161, v161, v192, s[46:47]
	v_mul_f32_e32 v192, v92, v161
	v_mul_f32_e32 v192, v168, v192
	v_cvt_pk_bf16_f32 v192, v192, s0
	global_store_short v[198:199], v192, off
	v_mul_f32_e32 v192, v64, v161
	v_mul_f32_e32 v192, v169, v192
	v_cvt_pk_bf16_f32 v192, v192, s0
	global_store_short v[198:199], v192, off offset:32
	v_mul_f32_e32 v192, v28, v161
	v_mul_f32_e32 v161, v12, v161
	v_mul_f32_e32 v192, v170, v192
	v_mul_f32_e32 v161, v171, v161
	v_cvt_pk_bf16_f32 v192, v192, s0
	v_cvt_pk_bf16_f32 v161, v161, s0
	global_store_short v[198:199], v192, off offset:64
	global_store_short v[198:199], v161, off offset:96
	v_mov_b32_e32 v198, v22
	v_mov_b32_e32 v199, v6
	v_pk_mul_f32 v[198:199], v[198:199], v[198:199]
	v_cmp_gt_f32_e32 vcc, s93, v194
	v_mov_b32_e32 v201, v198
	v_pk_add_f32 v[196:197], v[196:197], v[200:201]
	v_mov_b32_e32 v198, v203
	v_pk_add_f32 v[196:197], v[196:197], v[198:199]
	ds_bpermute_b32 v199, v175, v197
	ds_bpermute_b32 v198, v175, v196
	v_mul_f32_e32 v161, 0x4b800000, v194
	v_cndmask_b32_e32 v161, v194, v161, vcc
	v_rsq_f32_e32 v161, v161
	v_add_u32_e32 v194, 0x93, v160
	s_waitcnt lgkmcnt(0)
	v_pk_add_f32 v[196:197], v[196:197], v[198:199]
	ds_bpermute_b32 v199, v174, v197
	ds_bpermute_b32 v198, v174, v196
	v_mul_f32_e32 v192, 0x45800000, v161
	v_cndmask_b32_e32 v161, v161, v192, vcc
	v_ashrrev_i32_e32 v195, 31, v194
	v_mul_f32_e32 v192, v93, v161
	s_waitcnt lgkmcnt(0)
	v_pk_add_f32 v[196:197], v[196:197], v[198:199]
	ds_bpermute_b32 v199, v173, v197
	ds_bpermute_b32 v198, v173, v196
	v_lshlrev_b64 v[194:195], 12, v[194:195]
	v_mul_f32_e32 v192, v168, v192
	v_lshl_add_u64 v[194:195], v[158:159], 0, v[194:195]
	v_cvt_pk_bf16_f32 v192, v192, s0
	s_waitcnt lgkmcnt(0)
	v_pk_add_f32 v[196:197], v[196:197], v[198:199]
	ds_bpermute_b32 v199, v172, v197
	ds_bpermute_b32 v198, v172, v196
	global_store_short v[194:195], v192, off
	v_mul_f32_e32 v192, v65, v161
	v_mul_f32_e32 v192, v169, v192
	v_cvt_pk_bf16_f32 v192, v192, s0
	global_store_short v[194:195], v192, off offset:32
	v_mul_f32_e32 v192, v29, v161
	v_mul_f32_e32 v161, v13, v161
	v_mul_f32_e32 v161, v171, v161
	s_waitcnt lgkmcnt(0)
	v_pk_add_f32 v[196:197], v[196:197], v[198:199]
	v_cvt_pk_bf16_f32 v161, v161, s0
	v_pk_fma_f32 v[196:197], v[196:197], s[8:9], v[162:163] op_sel_hi:[1,0,0]
	global_store_short v[194:195], v161, off offset:96
	v_mul_f32_e32 v161, 0x4b800000, v197
	v_cmp_gt_f32_e64 s[46:47], s93, v197
	v_mul_f32_e32 v192, v170, v192
	v_cvt_pk_bf16_f32 v192, v192, s0
	v_cndmask_b32_e64 v161, v197, v161, s[46:47]
	v_rsq_f32_e32 v161, v161
	global_store_short v[194:195], v192, off offset:64
	v_add_u32_e32 v194, 0xa0, v160
	v_ashrrev_i32_e32 v195, 31, v194
	v_mul_f32_e32 v192, 0x45800000, v161
	v_cndmask_b32_e64 v161, v161, v192, s[46:47]
	v_mul_f32_e32 v192, v86, v161
	v_lshlrev_b64 v[194:195], 12, v[194:195]
	v_mul_f32_e32 v192, v168, v192
	v_lshl_add_u64 v[194:195], v[158:159], 0, v[194:195]
	v_cvt_pk_bf16_f32 v192, v192, s0
	global_store_short v[194:195], v192, off
	v_mul_f32_e32 v192, v54, v161
	v_mul_f32_e32 v192, v169, v192
	v_cvt_pk_bf16_f32 v192, v192, s0
	global_store_short v[194:195], v192, off offset:32
	v_mul_f32_e32 v192, v22, v161
	v_mul_f32_e32 v161, v6, v161
	v_mul_f32_e32 v161, v171, v161
	v_cvt_pk_bf16_f32 v161, v161, s0
	v_cmp_gt_f32_e32 vcc, s93, v196
	global_store_short v[194:195], v161, off offset:96
	v_mul_f32_e32 v161, 0x4b800000, v196
	v_cndmask_b32_e32 v161, v196, v161, vcc
	v_rsq_f32_e32 v161, v161
	v_mul_f32_e32 v192, v170, v192
	v_cvt_pk_bf16_f32 v192, v192, s0
	global_store_short v[194:195], v192, off offset:64
	v_mul_f32_e32 v192, 0x45800000, v161
	v_cndmask_b32_e32 v161, v161, v192, vcc
	v_add_u32_e32 v194, 0xa1, v160
	v_ashrrev_i32_e32 v195, 31, v194
	v_mul_f32_e32 v192, v87, v161
	v_lshlrev_b64 v[194:195], 12, v[194:195]
	v_mul_f32_e32 v192, v168, v192
	v_lshl_add_u64 v[194:195], v[158:159], 0, v[194:195]
	v_cvt_pk_bf16_f32 v192, v192, s0
	global_store_short v[194:195], v192, off
	v_mul_f32_e32 v192, v55, v161
	v_mul_f32_e32 v192, v169, v192
	v_cvt_pk_bf16_f32 v192, v192, s0
	global_store_short v[194:195], v192, off offset:32
	v_mul_f32_e32 v192, v23, v161
	v_mul_f32_e32 v161, v7, v161
	v_mul_f32_e32 v192, v170, v192
	v_mul_f32_e32 v161, v171, v161
	v_cvt_pk_bf16_f32 v192, v192, s0
	v_cvt_pk_bf16_f32 v161, v161, s0
	global_store_short v[194:195], v192, off offset:64
	global_store_short v[194:195], v161, off offset:96
	v_mov_b32_e32 v194, v88
	v_mov_b32_e32 v195, v56
	v_mov_b32_e32 v200, v89
	v_mov_b32_e32 v201, v57
	v_pk_mul_f32 v[194:195], v[194:195], v[194:195]
	v_mov_b32_e32 v196, v24
	v_mov_b32_e32 v197, v8
	v_pk_mul_f32 v[200:201], v[200:201], v[200:201]
	v_mov_b32_e32 v203, v9
	v_pk_mul_f32 v[196:197], v[196:197], v[196:197]
	v_pk_mul_f32 v[202:203], v[202:203], v[202:203]
	v_mov_b32_e32 v204, v200
	v_mov_b32_e32 v205, v194
	v_mov_b32_e32 v194, v201
	v_pk_add_f32 v[194:195], v[204:205], v[194:195]
	v_mov_b32_e32 v200, v202
	v_mov_b32_e32 v201, v196
	v_pk_add_f32 v[194:195], v[194:195], v[200:201]
	v_mov_b32_e32 v196, v203
	v_pk_add_f32 v[194:195], v[194:195], v[196:197]
	ds_bpermute_b32 v197, v175, v195
	ds_bpermute_b32 v196, v175, v194
	v_add_u32_e32 v198, 0xa2, v160
	v_ashrrev_i32_e32 v199, 31, v198
	v_lshlrev_b64 v[198:199], 12, v[198:199]
	v_lshl_add_u64 v[198:199], v[158:159], 0, v[198:199]
	s_waitcnt lgkmcnt(0)
; __device__ __forceinline__ unsigned f2bf(float f) { const __bf16 b = (__bf16)f; return (unsigned)__builtin_bit_cast(unsigned short, b); }
;     __device__ __forceinline__ void operator()(Acc& acc, int pm, int pn, int wr, int wc, int fr, int fq) const {
;     ...
;                     float ss = acc[ai][0][m][0][j] * acc[ai][0][m][0][j] + acc[ai][0][m][1][j] * acc[ai][0][m][1][j] +
;                                acc[ai][1][m][0][j] * acc[ai][1][m][0][j] + acc[ai][1][m][1][j] * acc[ai][1][m][1][j];
;                     ss += __shfl_xor(ss, 1); ss += __shfl_xor(ss, 2); ss += __shfl_xor(ss, 4); ss += __shfl_xor(ss, 8);
;                     const float rs = rsqrtf(ss * (1.0f / 64.0f) + EPSV);
;                     bf16_t* rp = qk + (size_t)(pm * 256 + ai * 128 + wr * 64 + m * 16 + fq * 4 + j) * 2048 + head * 64 + fr;
; #pragma unroll
;                     for (int bj = 0; bj < 2; ++bj)
; #pragma unroll
;                         for (int n = 0; n < 2; ++n) rp[bj * 32 + n * 16] = (bf16_t)f2bf(acc[ai][bj][m][n][j] * rs * gv[bj][n]);
;                 }
	v_pk_add_f32 v[194:195], v[194:195], v[196:197]
	ds_bpermute_b32 v197, v174, v195
	ds_bpermute_b32 v196, v174, v194
	v_mov_b32_e32 v200, v79
	v_mov_b32_e32 v201, v47
	v_pk_mul_f32 v[200:201], v[200:201], v[200:201]
	v_mov_b32_e32 v202, v19
	s_waitcnt lgkmcnt(0)
	v_pk_add_f32 v[194:195], v[194:195], v[196:197]
	ds_bpermute_b32 v197, v173, v195
	ds_bpermute_b32 v196, v173, v194
	v_mov_b32_e32 v203, v3
	v_pk_mul_f32 v[202:203], v[202:203], v[202:203]
	v_mov_b32_e32 v204, v200
	v_mov_b32_e32 v200, v202
	s_waitcnt lgkmcnt(0)
	v_pk_add_f32 v[194:195], v[194:195], v[196:197]
	ds_bpermute_b32 v197, v172, v195
	ds_bpermute_b32 v196, v172, v194
	v_mov_b32_e32 v202, v21
	s_waitcnt lgkmcnt(0)
	v_pk_add_f32 v[194:195], v[194:195], v[196:197]
	s_nop 0
	v_pk_fma_f32 v[194:195], v[194:195], s[8:9], v[162:163] op_sel_hi:[1,0,0]
	v_mov_b32_e32 v196, v78
	v_mul_f32_e32 v161, 0x4b800000, v195
	v_cmp_gt_f32_e64 s[46:47], s93, v195
	v_mov_b32_e32 v197, v46
	v_pk_mul_f32 v[196:197], v[196:197], v[196:197]
	v_cndmask_b32_e64 v161, v195, v161, s[46:47]
	v_rsq_f32_e32 v161, v161
	v_mov_b32_e32 v205, v196
	v_mov_b32_e32 v196, v201
	v_pk_add_f32 v[196:197], v[204:205], v[196:197]
	v_mul_f32_e32 v192, 0x45800000, v161
	v_cndmask_b32_e64 v161, v161, v192, s[46:47]
	v_mul_f32_e32 v192, v88, v161
	v_mul_f32_e32 v192, v168, v192
	v_cvt_pk_bf16_f32 v192, v192, s0
	global_store_short v[198:199], v192, off
	v_mul_f32_e32 v192, v56, v161
	v_mul_f32_e32 v192, v169, v192
	v_cvt_pk_bf16_f32 v192, v192, s0
	global_store_short v[198:199], v192, off offset:32
	v_mul_f32_e32 v192, v24, v161
	v_mul_f32_e32 v161, v8, v161
	v_mul_f32_e32 v192, v170, v192
	v_mul_f32_e32 v161, v171, v161
	v_cvt_pk_bf16_f32 v192, v192, s0
	v_cvt_pk_bf16_f32 v161, v161, s0
	global_store_short v[198:199], v192, off offset:64
	global_store_short v[198:199], v161, off offset:96
	v_mov_b32_e32 v198, v18
	v_mov_b32_e32 v199, v2
	v_pk_mul_f32 v[198:199], v[198:199], v[198:199]
	v_cmp_gt_f32_e32 vcc, s93, v194
	v_mov_b32_e32 v201, v198
	v_pk_add_f32 v[196:197], v[196:197], v[200:201]
	v_mov_b32_e32 v198, v203
	v_pk_add_f32 v[196:197], v[196:197], v[198:199]
	ds_bpermute_b32 v199, v175, v197
	ds_bpermute_b32 v198, v175, v196
	v_mul_f32_e32 v161, 0x4b800000, v194
	v_cndmask_b32_e32 v161, v194, v161, vcc
	v_rsq_f32_e32 v161, v161
	v_add_u32_e32 v194, 0xa3, v160
	s_waitcnt lgkmcnt(0)
	v_pk_add_f32 v[196:197], v[196:197], v[198:199]
	ds_bpermute_b32 v199, v174, v197
	ds_bpermute_b32 v198, v174, v196
	v_mul_f32_e32 v192, 0x45800000, v161
	v_cndmask_b32_e32 v161, v161, v192, vcc
	v_ashrrev_i32_e32 v195, 31, v194
	v_mul_f32_e32 v192, v89, v161
	s_waitcnt lgkmcnt(0)
	v_pk_add_f32 v[196:197], v[196:197], v[198:199]
	ds_bpermute_b32 v199, v173, v197
	ds_bpermute_b32 v198, v173, v196
	v_lshlrev_b64 v[194:195], 12, v[194:195]
	v_mul_f32_e32 v192, v168, v192
	v_lshl_add_u64 v[194:195], v[158:159], 0, v[194:195]
	v_cvt_pk_bf16_f32 v192, v192, s0
	s_waitcnt lgkmcnt(0)
	v_pk_add_f32 v[196:197], v[196:197], v[198:199]
	ds_bpermute_b32 v199, v172, v197
	ds_bpermute_b32 v198, v172, v196
	global_store_short v[194:195], v192, off
	v_mul_f32_e32 v192, v57, v161
	v_mul_f32_e32 v192, v169, v192
	v_cvt_pk_bf16_f32 v192, v192, s0
	global_store_short v[194:195], v192, off offset:32
	v_mul_f32_e32 v192, v25, v161
	v_mul_f32_e32 v161, v9, v161
	v_mul_f32_e32 v161, v171, v161
	s_waitcnt lgkmcnt(0)
; __device__ __forceinline__ unsigned f2bf(float f) { const __bf16 b = (__bf16)f; return (unsigned)__builtin_bit_cast(unsigned short, b); }
;     __device__ __forceinline__ void operator()(Acc& acc, int pm, int pn, int wr, int wc, int fr, int fq) const {
;     ...
;                     float ss = acc[ai][0][m][0][j] * acc[ai][0][m][0][j] + acc[ai][0][m][1][j] * acc[ai][0][m][1][j] +
;                                acc[ai][1][m][0][j] * acc[ai][1][m][0][j] + acc[ai][1][m][1][j] * acc[ai][1][m][1][j];
;                     ss += __shfl_xor(ss, 1); ss += __shfl_xor(ss, 2); ss += __shfl_xor(ss, 4); ss += __shfl_xor(ss, 8);
;                     const float rs = rsqrtf(ss * (1.0f / 64.0f) + EPSV);
;                     bf16_t* rp = qk + (size_t)(pm * 256 + ai * 128 + wr * 64 + m * 16 + fq * 4 + j) * 2048 + head * 64 + fr;
; #pragma unroll
;                     for (int bj = 0; bj < 2; ++bj)
; #pragma unroll
;                         for (int n = 0; n < 2; ++n) rp[bj * 32 + n * 16] = (bf16_t)f2bf(acc[ai][bj][m][n][j] * rs * gv[bj][n]);
;                 }
	v_pk_add_f32 v[196:197], v[196:197], v[198:199]
	v_cvt_pk_bf16_f32 v161, v161, s0
	v_pk_fma_f32 v[196:197], v[196:197], s[8:9], v[162:163] op_sel_hi:[1,0,0]
	global_store_short v[194:195], v161, off offset:96
	v_mul_f32_e32 v161, 0x4b800000, v197
	v_cmp_gt_f32_e64 s[46:47], s93, v197
	v_mul_f32_e32 v192, v170, v192
	v_cvt_pk_bf16_f32 v192, v192, s0
	v_cndmask_b32_e64 v161, v197, v161, s[46:47]
	v_rsq_f32_e32 v161, v161
	global_store_short v[194:195], v192, off offset:64
	v_add_u32_e32 v194, 0xb0, v160
	v_ashrrev_i32_e32 v195, 31, v194
	v_mul_f32_e32 v192, 0x45800000, v161
	v_cndmask_b32_e64 v161, v161, v192, s[46:47]
	v_mul_f32_e32 v192, v78, v161
	v_lshlrev_b64 v[194:195], 12, v[194:195]
	v_mul_f32_e32 v192, v168, v192
	v_lshl_add_u64 v[194:195], v[158:159], 0, v[194:195]
	v_cvt_pk_bf16_f32 v192, v192, s0
	global_store_short v[194:195], v192, off
	v_mul_f32_e32 v192, v46, v161
	v_mul_f32_e32 v192, v169, v192
	v_cvt_pk_bf16_f32 v192, v192, s0
	global_store_short v[194:195], v192, off offset:32
	v_mul_f32_e32 v192, v18, v161
	v_mul_f32_e32 v161, v2, v161
	v_mul_f32_e32 v161, v171, v161
	v_cvt_pk_bf16_f32 v161, v161, s0
	v_cmp_gt_f32_e32 vcc, s93, v196
	global_store_short v[194:195], v161, off offset:96
	v_mul_f32_e32 v161, 0x4b800000, v196
	v_cndmask_b32_e32 v161, v196, v161, vcc
	v_rsq_f32_e32 v161, v161
	v_mul_f32_e32 v192, v170, v192
	v_cvt_pk_bf16_f32 v192, v192, s0
	global_store_short v[194:195], v192, off offset:64
	v_mul_f32_e32 v192, 0x45800000, v161
	v_cndmask_b32_e32 v161, v161, v192, vcc
	v_add_u32_e32 v194, 0xb1, v160
	v_ashrrev_i32_e32 v195, 31, v194
	v_mul_f32_e32 v192, v79, v161
	v_lshlrev_b64 v[194:195], 12, v[194:195]
	v_mul_f32_e32 v192, v168, v192
	v_lshl_add_u64 v[194:195], v[158:159], 0, v[194:195]
	v_cvt_pk_bf16_f32 v192, v192, s0
	global_store_short v[194:195], v192, off
	v_mul_f32_e32 v192, v47, v161
	v_mul_f32_e32 v192, v169, v192
	v_cvt_pk_bf16_f32 v192, v192, s0
	global_store_short v[194:195], v192, off offset:32
	v_mul_f32_e32 v192, v19, v161
	v_mul_f32_e32 v161, v3, v161
	v_mul_f32_e32 v192, v170, v192
	v_mul_f32_e32 v161, v171, v161
	v_cvt_pk_bf16_f32 v192, v192, s0
	v_cvt_pk_bf16_f32 v161, v161, s0
	global_store_short v[194:195], v192, off offset:64
	global_store_short v[194:195], v161, off offset:96
	v_mov_b32_e32 v194, v80
	v_mov_b32_e32 v195, v48
	v_mov_b32_e32 v200, v81
	v_mov_b32_e32 v201, v49
	v_pk_mul_f32 v[194:195], v[194:195], v[194:195]
	v_mov_b32_e32 v196, v20
	v_mov_b32_e32 v197, v4
	v_pk_mul_f32 v[200:201], v[200:201], v[200:201]
	v_mov_b32_e32 v203, v5
	v_pk_mul_f32 v[196:197], v[196:197], v[196:197]
	v_pk_mul_f32 v[202:203], v[202:203], v[202:203]
	v_mov_b32_e32 v204, v200
	v_mov_b32_e32 v205, v194
	v_mov_b32_e32 v194, v201
	v_pk_add_f32 v[194:195], v[204:205], v[194:195]
	v_mov_b32_e32 v200, v202
	v_mov_b32_e32 v201, v196
	v_pk_add_f32 v[194:195], v[194:195], v[200:201]
	v_mov_b32_e32 v196, v203
	v_pk_add_f32 v[194:195], v[194:195], v[196:197]
	ds_bpermute_b32 v197, v175, v195
	ds_bpermute_b32 v196, v175, v194
	v_add_u32_e32 v198, 0xb2, v160
	v_ashrrev_i32_e32 v199, 31, v198
	v_lshlrev_b64 v[198:199], 12, v[198:199]
	v_lshl_add_u64 v[198:199], v[158:159], 0, v[198:199]
	s_waitcnt lgkmcnt(0)
	v_pk_add_f32 v[194:195], v[194:195], v[196:197]
	ds_bpermute_b32 v175, v174, v195
	ds_bpermute_b32 v174, v174, v194
	v_add_u32_e32 v160, 0xb3, v160
	s_waitcnt lgkmcnt(0)
	v_pk_add_f32 v[174:175], v[194:195], v[174:175]
	ds_bpermute_b32 v195, v173, v175
	ds_bpermute_b32 v194, v173, v174
	s_waitcnt lgkmcnt(0)
	v_pk_add_f32 v[174:175], v[174:175], v[194:195]
	ds_bpermute_b32 v173, v172, v175
	ds_bpermute_b32 v172, v172, v174
	s_waitcnt lgkmcnt(0)
	v_pk_add_f32 v[172:173], v[174:175], v[172:173]
	s_nop 0
	v_pk_fma_f32 v[162:163], v[172:173], s[8:9], v[162:163] op_sel_hi:[1,0,0]
	s_nop 0
	v_mul_f32_e32 v161, 0x4b800000, v163
	v_cmp_gt_f32_e64 s[46:47], s93, v163
	v_cmp_gt_f32_e32 vcc, s93, v162
	s_nop 0
	v_cndmask_b32_e64 v161, v163, v161, s[46:47]
	v_rsq_f32_e32 v161, v161
	s_nop 0
	v_mul_f32_e32 v163, 0x45800000, v161
	v_cndmask_b32_e64 v161, v161, v163, s[46:47]
	v_mul_f32_e32 v163, v80, v161
	v_mul_f32_e32 v163, v168, v163
	v_cvt_pk_bf16_f32 v163, v163, s0
	global_store_short v[198:199], v163, off
	v_mul_f32_e32 v163, v48, v161
	v_mul_f32_e32 v163, v169, v163
	v_cvt_pk_bf16_f32 v163, v163, s0
	global_store_short v[198:199], v163, off offset:32
	v_mul_f32_e32 v163, v20, v161
	v_mul_f32_e32 v161, v4, v161
	v_mul_f32_e32 v161, v171, v161
	v_cvt_pk_bf16_f32 v161, v161, s0
	global_store_short v[198:199], v161, off offset:96
	v_mul_f32_e32 v161, 0x4b800000, v162
	v_cndmask_b32_e32 v161, v162, v161, vcc
	v_rsq_f32_e32 v161, v161
	v_mul_f32_e32 v163, v170, v163
	v_cvt_pk_bf16_f32 v163, v163, s0
	global_store_short v[198:199], v163, off offset:64
	v_mul_f32_e32 v162, 0x45800000, v161
	v_cndmask_b32_e32 v162, v161, v162, vcc
	v_ashrrev_i32_e32 v161, 31, v160
	v_lshlrev_b64 v[160:161], 12, v[160:161]
	v_lshl_add_u64 v[158:159], v[158:159], 0, v[160:161]
	v_mul_f32_e32 v160, v81, v162
	v_mul_f32_e32 v160, v168, v160
	v_cvt_pk_bf16_f32 v160, v160, s0
	global_store_short v[158:159], v160, off
	v_mul_f32_e32 v160, v49, v162
	v_mul_f32_e32 v160, v169, v160
	v_cvt_pk_bf16_f32 v160, v160, s0
	global_store_short v[158:159], v160, off offset:32
	v_mul_f32_e32 v160, v21, v162
	v_mul_f32_e32 v160, v170, v160
	v_cvt_pk_bf16_f32 v160, v160, s0
	global_store_short v[158:159], v160, off offset:64
	v_mul_f32_e32 v160, v5, v162
	v_mul_f32_e32 v160, v171, v160
	v_cvt_pk_bf16_f32 v160, v160, s0
	global_store_short v[158:159], v160, off offset:96

;     ...
;     for (int r = rbeg + gw; r < nrows; r += nw) {
;         const float* xp = (r < T_LAT) ? xlat + (size_t)r * DM : xctx + (size_t)(r - T_LAT) * DM;
;         const int m = (r < T_LAT) ? (r >> 12) : 8;
;         const float* mv = p.modv + ((size_t)layer * 9 + m) * 6144 + shift_i * 1024;
;         f32x4 v[4];
;         float ss = 0.f;
; #pragma unroll
;         for (int i = 0; i < 4; ++i) {
;             v[i] = *reinterpret_cast<const f32x4*>(xp + (i * 64 + lane) * 4);
;             ss += v[i][0] * v[i][0] + v[i][1] * v[i][1] + v[i][2] * v[i][2] + v[i][3] * v[i][3];
;         }
; #pragma unroll
;         for (int o = 32; o >= 1; o >>= 1) ss += __shfl_xor(ss, o);
;         const float rstd = rsqrtf(ss * (1.0f / 1024.0f) + EPSV);
;         bf16_t* hp = p.hbuf + (size_t)r * DM;
; #pragma unroll
;         for (int i = 0; i < 4; ++i) {
;             const int col = (i * 64 + lane) * 4;
;             f32x4 gg = *reinterpret_cast<const f32x4*>(g + col);
;             f32x4 sh = *reinterpret_cast<const f32x4*>(mv + col);
;             f32x4 sc = *reinterpret_cast<const f32x4*>(mv + 1024 + col);
;             float o0 = v[i][0] * rstd * gg[0] * (1.f + sc[0]) + sh[0];
;             float o1 = v[i][1] * rstd * gg[1] * (1.f + sc[1]) + sh[1];
;             float o2 = v[i][2] * rstd * gg[2] * (1.f + sc[2]) + sh[2];
;             float o3 = v[i][3] * rstd * gg[3] * (1.f + sc[3]) + sh[3];
;             u32x2 o = {pack2(o0, o1), pack2(o2, o3)};
;             *reinterpret_cast<u32x2*>(hp + col) = o;
;         }
.LBB0_1483:
	s_or_b64 exec, exec, s[14:15]
	v_mov_b32_e32 v29, v0
	v_lshl_add_u64 v[2:3], v[2:3], 0, v[28:29]
	global_load_dwordx4 v[14:17], v[2:3], off
	global_load_dwordx4 v[10:13], v[2:3], off offset:1024
	global_load_dwordx4 v[192:195], v[2:3], off offset:2048
	global_load_dwordx4 v[196:199], v[2:3], off offset:3072
	global_load_dwordx4 v[200:203], v[20:21], off
	global_load_dwordx4 v[204:207], v[20:21], off offset:1024
	global_load_dwordx4 v[208:211], v[20:21], off offset:2048
	global_load_dwordx4 v[212:215], v[20:21], off offset:3072
	v_min_i32_e32 v4, 0x8000, v4
	v_ashrrev_i32_e32 v4, 12, v4
	v_readlane_b32 s56, v254, 6
	v_ashrrev_i32_e32 v5, 31, v4
	v_readlane_b32 s62, v254, 12
	v_readlane_b32 s63, v254, 13
	v_lshl_add_u64 v[4:5], v[4:5], 0, s[20:21]
	s_movk_i32 s5, 0x6000
	v_mov_b64_e32 v[6:7], s[62:63]
	v_mad_u64_u32 v[40:41], s[0:1], v4, s5, v[6:7]
	v_mad_i32_i24 v41, v5, s5, v41
	v_lshlrev_b64 v[60:61], 11, v[42:43]
	v_lshl_add_u64 v[42:43], v[40:41], 0, s[22:23]
	v_lshl_add_u64 v[248:249], v[40:41], 0, s[18:19]
	v_mov_b32_e32 v33, v0
	v_mov_b32_e32 v35, v0
	v_mov_b32_e32 v242, v30
	v_mov_b32_e32 v243, v0
	v_lshl_add_u64 v[240:241], v[248:249], 0, v[28:29]
	global_load_dwordx4 v[52:55], v[240:241], off
	v_lshl_add_u64 v[240:241], v[42:43], 0, v[28:29]
	global_load_dwordx4 v[56:59], v[240:241], off
	v_lshl_add_u64 v[240:241], v[248:249], 0, v[242:243]
	global_load_dwordx4 v[216:219], v[240:241], off
	v_lshl_add_u64 v[240:241], v[42:43], 0, v[242:243]
	global_load_dwordx4 v[220:223], v[240:241], off
	v_lshl_add_u64 v[240:241], v[248:249], 0, v[32:33]
	global_load_dwordx4 v[224:227], v[240:241], off
	v_lshl_add_u64 v[240:241], v[42:43], 0, v[32:33]
	global_load_dwordx4 v[228:231], v[240:241], off
	v_lshl_add_u64 v[240:241], v[248:249], 0, v[34:35]
	global_load_dwordx4 v[232:235], v[240:241], off
	v_lshl_add_u64 v[240:241], v[42:43], 0, v[34:35]
	global_load_dwordx4 v[236:239], v[240:241], off
	v_add_u32_e32 v24, s38, v24
	v_lshl_add_u64 v[18:19], v[18:19], 0, s[38:39]
	v_lshl_add_u64 v[26:27], v[26:27], 0, s[16:17]
	v_readlane_b32 s57, v254, 7
	v_readlane_b32 s58, v254, 8
	v_readlane_b32 s59, v254, 9
	v_readlane_b32 s60, v254, 10
	v_readlane_b32 s61, v254, 11
	s_waitcnt vmcnt(14)
	v_mov_b32_e32 v6, v15
	v_mov_b32_e32 v7, v11
	v_mov_b32_e32 v4, v14
	v_mov_b32_e32 v5, v10
	v_pk_mul_f32 v[6:7], v[6:7], v[6:7]
	s_nop 0
	v_pk_fma_f32 v[4:5], v[4:5], v[4:5], v[6:7]
	v_mov_b32_e32 v6, v16
	v_mov_b32_e32 v7, v12
	v_pk_fma_f32 v[4:5], v[6:7], v[6:7], v[4:5]
	v_mov_b32_e32 v6, v17
	v_mov_b32_e32 v7, v13
	v_pk_fma_f32 v[38:39], v[6:7], v[6:7], v[4:5]
	s_waitcnt vmcnt(12)
	v_mov_b32_e32 v6, v192
	v_mov_b32_e32 v7, v193
	v_mov_b32_e32 v8, v194
	v_mov_b32_e32 v9, v195
	v_mov_b32_e32 v2, v196
	v_mov_b32_e32 v3, v197
	v_mov_b32_e32 v4, v198
	v_mov_b32_e32 v5, v199
	v_add_f32_e32 v25, v38, v39
	v_mov_b32_e32 v50, v7
	v_mov_b32_e32 v51, v3
	v_mov_b32_e32 v48, v6
	v_mov_b32_e32 v49, v2
	v_pk_mul_f32 v[50:51], v[50:51], v[50:51]
	s_waitcnt vmcnt(6)
	v_pk_add_f32 v[40:41], v[56:57], 1.0 op_sel_hi:[1,0]
	v_pk_fma_f32 v[48:49], v[48:49], v[48:49], v[50:51]
	v_mov_b32_e32 v50, v8
	v_mov_b32_e32 v51, v4
	v_pk_fma_f32 v[48:49], v[50:51], v[50:51], v[48:49]
	v_mov_b32_e32 v50, v9
	v_mov_b32_e32 v51, v5
	v_pk_fma_f32 v[48:49], v[50:51], v[50:51], v[48:49]
	s_nop 0
	v_add_f32_e32 v25, v25, v48
	v_add_f32_e32 v25, v25, v49
	ds_bpermute_b32 v31, v1, v25
	s_waitcnt lgkmcnt(0)
	v_add_f32_e32 v25, v25, v31
	ds_bpermute_b32 v31, v37, v25
	s_waitcnt lgkmcnt(0)
	v_add_f32_e32 v25, v25, v31
	ds_bpermute_b32 v31, v44, v25
	s_waitcnt lgkmcnt(0)
	v_add_f32_e32 v25, v25, v31
	ds_bpermute_b32 v31, v45, v25
	s_waitcnt lgkmcnt(0)
	v_add_f32_e32 v25, v25, v31
	ds_bpermute_b32 v31, v46, v25
	s_waitcnt lgkmcnt(0)
	v_add_f32_e32 v25, v25, v31
	ds_bpermute_b32 v31, v47, v25
	s_waitcnt lgkmcnt(0)
	v_add_f32_e32 v25, v25, v31
	v_fmamk_f32 v25, v25, 0x3a800000, v177
	v_cmp_gt_f32_e32 vcc, s93, v25
	v_mul_f32_e32 v31, 0x4b800000, v25
	s_nop 0
	v_cndmask_b32_e32 v25, v25, v31, vcc
	v_rsq_f32_e32 v25, v25
	s_nop 0
	v_mul_f32_e32 v31, 0x45800000, v25
	v_cndmask_b32_e32 v36, v25, v31, vcc
	v_pk_mul_f32 v[14:15], v[14:15], v[36:37] op_sel_hi:[1,0]
	v_pk_mul_f32 v[16:17], v[16:17], v[36:37] op_sel_hi:[1,0]
	v_mov_b32_e32 v31, v0
	v_pk_mul_f32 v[10:11], v[10:11], v[36:37] op_sel_hi:[1,0]
	v_pk_mul_f32 v[12:13], v[12:13], v[36:37] op_sel_hi:[1,0]
	v_pk_mul_f32 v[6:7], v[6:7], v[36:37] op_sel_hi:[1,0]
	v_pk_mul_f32 v[8:9], v[8:9], v[36:37] op_sel_hi:[1,0]
	v_pk_mul_f32 v[2:3], v[2:3], v[36:37] op_sel_hi:[1,0]
	v_pk_mul_f32 v[4:5], v[4:5], v[36:37] op_sel_hi:[1,0]
	s_waitcnt vmcnt(0)
	v_pk_mul_f32 v[14:15], v[200:201], v[14:15]
	s_nop 0
	v_pk_fma_f32 v[14:15], v[40:41], v[14:15], v[52:53]
	v_pk_mul_f32 v[16:17], v[202:203], v[16:17]
	v_pk_add_f32 v[40:41], v[58:59], 1.0 op_sel_hi:[1,0]
	v_cvt_pk_bf16_f32 v14, v14, v15
	v_pk_fma_f32 v[16:17], v[40:41], v[16:17], v[54:55]
	v_lshl_add_u64 v[40:41], v[22:23], 0, v[60:61]
	v_cvt_pk_bf16_f32 v15, v16, v17
	global_store_dwordx2 v[40:41], v[14:15], off
	v_pk_mul_f32 v[10:11], v[204:205], v[10:11]
	v_pk_mul_f32 v[12:13], v[206:207], v[12:13]
	v_pk_add_f32 v[14:15], v[220:221], 1.0 op_sel_hi:[1,0]
	s_nop 0
	v_pk_fma_f32 v[10:11], v[14:15], v[10:11], v[216:217]
	v_pk_add_f32 v[14:15], v[222:223], 1.0 op_sel_hi:[1,0]
	v_cvt_pk_bf16_f32 v10, v10, v11
	v_pk_fma_f32 v[12:13], v[14:15], v[12:13], v[218:219]
	s_nop 0
	v_cvt_pk_bf16_f32 v11, v12, v13
	global_store_dwordx2 v[40:41], v[10:11], off offset:512
	v_pk_mul_f32 v[6:7], v[208:209], v[6:7]
	v_pk_add_f32 v[10:11], v[228:229], 1.0 op_sel_hi:[1,0]
	v_pk_mul_f32 v[8:9], v[210:211], v[8:9]
	v_pk_fma_f32 v[6:7], v[10:11], v[6:7], v[224:225]
	v_pk_add_f32 v[10:11], v[230:231], 1.0 op_sel_hi:[1,0]
	v_cvt_pk_bf16_f32 v6, v6, v7
	v_pk_fma_f32 v[8:9], v[10:11], v[8:9], v[226:227]
	s_nop 0
	v_cvt_pk_bf16_f32 v7, v8, v9
	global_store_dwordx2 v[40:41], v[6:7], off offset:1024
	v_pk_mul_f32 v[2:3], v[2:3], v[212:213]
	v_pk_mul_f32 v[4:5], v[4:5], v[214:215]
	v_pk_add_f32 v[6:7], v[236:237], 1.0 op_sel_hi:[1,0]
	s_nop 0
	v_pk_fma_f32 v[2:3], v[2:3], v[6:7], v[232:233]
	v_pk_add_f32 v[6:7], v[238:239], 1.0 op_sel_hi:[1,0]
	v_cvt_pk_bf16_f32 v2, v2, v3
	v_pk_fma_f32 v[4:5], v[4:5], v[6:7], v[234:235]
	s_nop 0
	v_cvt_pk_bf16_f32 v3, v4, v5
	global_store_dwordx2 v[40:41], v[2:3], off offset:1536
	v_add_u32_e32 v2, 0x8000, v24
	v_cmp_lt_i32_e32 vcc, s94, v2
	s_or_b64 s[12:13], vcc, s[12:13]
	s_andn2_b64 exec, exec, s[12:13]
	s_cbranch_execz .LBB0_1486
